# GEMM calls: one static s_setprio 1 for the wave half that enters the K-loop a phase later, reset at call end
# baseline (speedup 1.0000x reference)
; #define PG8_STAGE(bufoff, gbase, voff) do { _Pragma("unroll") for (int _i = 0; _i < 2; ++_i) \
;         __builtin_amdgcn_global_load_lds((const unsigned*)((const char*)(gbase) + (voff)[_i]), (PG8_LAS unsigned*)(lds + (bufoff) + ldsw + _i * 8192), 16, 0, 0); } while (0)
; #define PG8_BAR __builtin_amdgcn_s_barrier()
; template <class Epi, class Sched, bool STAMP = false>
; __device__ __forceinline__ void gemm_phase(PG8_LAS unsigned char* lds, const Gemm g, const Sched& S, const Epi& E, unsigned long long* stamps) {
;     int tid_ = threadIdx.x; asm volatile("" : "+v"(tid_)); const int tid = tid_, wid = __builtin_amdgcn_readfirstlane(tid >> 6), lane = tid & 63, wr = wid >> 2, wc = wid & 3, fr = lane & 15, fq = lane >> 4;
;     const int K = g.K, nt = K / BK, LD = g.ld;
;     unsigned voffA[2], voffB[2];
; #pragma unroll
;     for (int i = 0; i < 2; ++i) { int R, C; stage_rc(tid * 16 + i * 8192, R, C); const int Rb = Epi::PERM ? ((R & ~31) + perm32(R & 31)) : R;
;         voffA[i] = (unsigned)(R * LD + C) * 2u; voffB[i] = (unsigned)(Rb * LD + C) * 2u; }
;     const size_t kstep = (size_t)(BK * 2);
;     const size_t hstep = (size_t)HALF * LD * 2;
;     const size_t tstep = 2 * hstep;
;     const unsigned ldsw = (unsigned)wid * 1024u;
;     const int aoff = lds_byte(wr * 64 + fr, fq * 8), boff = lds_byte(wc * 32 + fr, fq * 8);
;     ...
;     Unit cur, nxt; int ui = 0;
;     if (!S.next(0, cur)) return;
;     f32x4 acc[2][2][4][2];
; #pragma unroll
;     for (int a = 0; a < 2; ++a)
; #pragma unroll
;         for (int b = 0; b < 2; ++b)
; #pragma unroll
;             for (int m = 0; m < 4; ++m)
; #pragma unroll
;                 for (int n = 0; n < 2; ++n) acc[a][b][m][n] = (f32x4){0.f, 0.f, 0.f, 0.f};
;     bf16x8 At[4][2], B0[2][2], B1[2][2];
;     const char* cA = (const char*)g.A + (size_t)cur.pm * tstep; const char* cB = (const char*)g.Bt + (size_t)cur.pn * tstep;
;     S.a_ready(cur);
;     PG8_STAGE(PG8_SB(0, 0), cB, voffB); PG8_STAGE(PG8_SA(0, 0), cA, voffA); PG8_STAGE(PG8_SB(0, 1), cB + hstep, voffB); PG8_STAGE(PG8_SA(0, 1), cA + hstep, voffA);
;     if (wr == 1) PG8_BAR;
; __global__ void __launch_bounds__(512, 2) mega_fwd(Params prm) {
;     ...
;     for (int ph = 0; ph < 28; ++ph) {
;         const int l = ph >= 14 ? 1 : 0, k = ph - 14 * l;
;         switch (k) {
.LBB0_32:
	v_readlane_b32 s2, v242, 19
	s_cmp_lt_u32 s2, 14
	s_cselect_b64 s[0:1], -1, 0
	s_cmp_gt_u32 s2, 13
	v_writelane_b32 v242, s0, 35
	s_cselect_b64 s[34:35], -1, 0
	s_mov_b64 s[36:37], 0
	v_writelane_b32 v242, s1, 36
	s_and_b64 s[0:1], s[34:35], exec
	s_cselect_b32 s0, -14, 0
	s_add_i32 s65, s0, s2
	s_mov_b64 s[2:3], 0
	v_writelane_b32 v242, s2, 37
	s_mov_b64 s[0:1], -1
	s_cmp_lt_i32 s65, 6
	v_writelane_b32 v242, s3, 38
	v_writelane_b32 v242, s88, 39
	s_nop 1
	v_writelane_b32 v242, s89, 40
	s_cbranch_scc1 .LBB0_548
	s_cmp_gt_i32 s65, 8
	s_cbranch_scc0 .LBB0_52
	s_cmp_gt_i32 s65, 10
	s_cbranch_scc0 .LBB0_62
	s_cmp_gt_i32 s65, 11
	s_cbranch_scc0 .LBB0_63
	s_cmp_eq_u32 s65, 12
	s_cbranch_scc0 .LBB0_120
	s_mov_b32 s3, s87
	s_mov_b32 s2, s86
	s_mov_b32 s10, s90
	v_mov_b32_e32 v14, v184
	s_cmpk_gt_i32 s10, 0x43f
	v_readfirstlane_b32 s36, v14
	s_cbranch_scc1 .LBB0_49
	v_lshlrev_b32_e32 v0, 4, v14
	v_add_u32_e32 v1, 0x2000, v0
	v_ashrrev_i32_e32 v2, 31, v1
	v_lshrrev_b32_e32 v2, 22, v2
	v_add_u32_e32 v2, v1, v2
	v_ashrrev_i32_e32 v8, 10, v2
	v_mul_i32_i24_e32 v2, 0x400, v8
	v_sub_u32_e32 v1, v1, v2
	v_lshrrev_b32_e32 v2, 4, v1
	v_bitop3_b32 v1, v2, v1, 32 bitop3:0x6c
	v_ashrrev_i32_e32 v2, 31, v1
	v_lshrrev_b32_e32 v2, 26, v2
	v_add_u32_e32 v2, v1, v2
	v_lshlrev_b32_e32 v3, 3, v8
	v_ashrrev_i32_e32 v9, 6, v2
	v_and_b32_e32 v3, -16, v3
	v_add_u32_e32 v3, v9, v3
	v_and_b32_e32 v4, 3, v9
	s_mov_b32 s0, 0x1fffe0
	v_lshrrev_b32_e32 v5, 2, v3
	v_lshlrev_b32_e32 v6, 1, v3
	v_and_b32_e32 v2, 0xc0, v2
	v_and_or_b32 v4, v3, s0, v4
	v_and_b32_e32 v5, 4, v5
	v_and_b32_e32 v6, 24, v6
	v_sub_u32_e32 v1, v1, v2
	v_or3_b32 v4, v4, v5, v6
	v_lshlrev_b32_e32 v5, 5, v8
	v_ashrrev_i16_sdwa v1, v188, sext(v1) dst_sel:DWORD dst_unused:UNUSED_PAD src0_sel:DWORD src1_sel:BYTE_0
	v_and_b32_e32 v5, 32, v5
	v_bfe_i32 v10, v1, 0, 16
	v_add_lshl_u32 v1, v5, v10, 1
	v_lshl_add_u32 v148, v4, 11, v1
	v_lshl_add_u32 v150, v3, 11, v1
	v_bfe_i32 v1, v14, 27, 1
	v_lshrrev_b32_e32 v1, 22, v1
	v_add_u32_e32 v1, v0, v1
	v_and_b32_e32 v1, 0xfffffc00, v1
	v_sub_u32_e32 v0, v0, v1
	v_lshrrev_b32_e32 v1, 4, v0
	v_ashrrev_i32_e32 v2, 31, v14
	v_bitop3_b32 v0, v1, v0, 32 bitop3:0x6c
	v_lshrrev_b32_e32 v2, 26, v2
	v_ashrrev_i32_e32 v1, 31, v0
	v_add_u32_e32 v2, v14, v2
	s_add_u32 s37, s2, 0x2200000
	v_lshrrev_b32_e32 v1, 26, v1
	s_waitcnt lgkmcnt(0)
	v_ashrrev_i32_e32 v12, 6, v2
	s_addc_u32 s40, s3, 0
	v_add_u32_e32 v1, v0, v1
	v_lshlrev_b32_e32 v2, 3, v12
	s_add_u32 s41, s2, 0x1000000
	v_ashrrev_i32_e32 v11, 6, v1
	v_and_b32_e32 v2, -16, v2
	s_addc_u32 s42, s3, 0
	v_add_u32_e32 v2, v11, v2
	v_and_b32_e32 v3, 3, v11
	s_ashr_i32 s44, s10, 31
	v_and_or_b32 v3, v2, s0, v3
	s_lshr_b32 s0, s44, 29
	s_add_i32 s0, s10, s0
	s_ashr_i32 s4, s36, 6
	s_ashr_i32 s1, s0, 3
	s_and_b32 s0, s0, -8
	s_ashr_i32 s5, s36, 8
	s_lshl_b32 s43, s4, 10
	s_sub_i32 s0, s10, s0
	s_cmp_lt_i32 s0, 0
	s_movk_i32 s6, 0x89
	s_cselect_b32 s6, s6, 0x88
	s_mul_i32 s0, s6, s0
	s_add_i32 s0, s0, s1
	s_ashr_i32 s1, s0, 31
	s_lshr_b32 s1, s1, 25
	v_lshrrev_b32_e32 v4, 2, v2
	v_lshlrev_b32_e32 v5, 1, v2
	v_and_b32_e32 v1, 0xc0, v1
	s_add_i32 s1, s0, s1
	v_and_b32_e32 v4, 4, v4
	v_and_b32_e32 v5, 24, v5
	v_sub_u32_e32 v0, v0, v1
	s_ashr_i32 s6, s1, 7
	v_or3_b32 v3, v3, v4, v5
	v_lshlrev_b32_e32 v4, 5, v12
	v_ashrrev_i16_sdwa v0, v188, sext(v0) dst_sel:DWORD dst_unused:UNUSED_PAD src0_sel:DWORD src1_sel:BYTE_0
	s_lshl_b32 s6, s6, 3
	v_and_b32_e32 v4, 32, v4
	v_bfe_i32 v13, v0, 0, 16
	s_sub_i32 s7, 0x44, s6
	v_add_lshl_u32 v0, v4, v13, 1
	s_min_u32 s7, s7, 8
	s_and_b32 s1, s1, 0xffffff80
	v_lshl_add_u32 v128, v3, 11, v0
	s_sub_i32 s12, s0, s1
	v_cvt_f32_ubyte0_e32 v3, s7
	v_cvt_f32_i32_e32 v1, s12
	v_rcp_iflag_f32_e32 v4, v3
	v_lshl_add_u32 v152, v2, 11, v0
	s_ashr_i32 s0, s12, 30
	s_or_b32 s13, s0, 1
	v_mul_f32_e32 v0, v1, v4
	v_trunc_f32_e32 v0, v0
	v_fma_f32 v1, -v0, v3, v1
	v_cvt_i32_f32_e32 v0, v0
	v_cmp_ge_f32_e64 s[0:1], |v1|, v3
	s_and_b64 s[0:1], s[0:1], exec
	s_cselect_b32 s0, s13, 0
	v_readfirstlane_b32 s1, v0
	s_add_i32 s0, s1, s0
	s_mul_i32 s1, s0, s7
	s_sub_i32 s1, s12, s1
	s_sext_i32_i8 s1, s1
	s_add_i32 s22, s6, s1
	s_ashr_i32 s23, s22, 31
	s_bfe_i64 s[12:13], s[0:1], 0x80000
	s_lshl_b64 s[6:7], s[22:23], 19
	s_lshl_b64 s[12:13], s[12:13], 19
	s_add_u32 s26, s41, s12
	s_addc_u32 s27, s42, s13
	s_add_i32 s23, s43, 0
	s_add_i32 m0, s23, 0x10000
	v_mov_b32_e32 v149, v129
	global_load_lds_dwordx4 v128, s[26:27]
	s_add_i32 m0, s23, 0x12000
	s_add_u32 s24, s37, s6
	global_load_lds_dwordx4 v148, s[26:27]
	s_addc_u32 s25, s40, s7
	s_mov_b32 m0, s23
	s_add_i32 s45, s23, 0x2000
	global_load_lds_dwordx4 v152, s[24:25]
	s_mov_b32 m0, s45
	s_add_u32 s6, s26, 0x40000
	global_load_lds_dwordx4 v150, s[24:25]
	s_addc_u32 s7, s27, 0
	s_add_i32 m0, s23, 0x14000
	v_mov_b32_e32 v153, v129
	global_load_lds_dwordx4 v128, s[6:7]
	s_add_i32 m0, s23, 0x16000
	v_mov_b32_e32 v151, v129
	global_load_lds_dwordx4 v148, s[6:7]
	s_add_u32 s6, s24, 0x40000
	s_addc_u32 s7, s25, 0
	s_add_i32 s46, s23, 0x4000
	s_mov_b32 m0, s46
	s_add_i32 s47, s23, 0x6000
	global_load_lds_dwordx4 v152, s[6:7]
	s_mov_b32 m0, s47
	s_mov_b32 s63, s65
	global_load_lds_dwordx4 v150, s[6:7]
	v_lshl_add_u64 v[6:7], s[26:27], 0, v[128:129]
	v_lshl_add_u64 v[4:5], s[26:27], 0, v[148:149]
	v_lshl_add_u64 v[2:3], s[24:25], 0, v[152:153]
	s_cmp_lg_u32 s5, 1
	v_lshl_add_u64 v[0:1], s[24:25], 0, v[150:151]
	s_cbranch_scc1 .LBB0_40
	s_barrier
	s_setprio 1

; #define PG8_WAIT_V(n) asm volatile("s_waitcnt vmcnt(" #n ")" ::: "memory")
; #define PG8_BAR __builtin_amdgcn_s_barrier()
; template <class Epi, class Sched, bool STAMP = false>
; __device__ __forceinline__ void gemm_phase(PG8_LAS unsigned char* lds, const Gemm g, const Sched& S, const Epi& E, unsigned long long* stamps) {
;     ...
;     PG8_WAIT_V(0);
;     if (wr == 0) PG8_BAR;
;     PG8_BAR;
.LBB0_48:
	s_setprio 0
	v_readlane_b32 s46, v242, 24
	v_readlane_b32 s47, v242, 25
	v_readlane_b32 s39, v242, 28
	s_movk_i32 s58, 0xff60
	s_mov_b32 s38, 0x1ffff
	s_mov_b32 s65, s63
	s_barrier

; #define PG8_BAR __builtin_amdgcn_s_barrier()
; #define INP(p, i) ldp((p).tbl, i)
;     __device__ bool next(int i, pg8::Unit& u) const { if (i != 0 || !valid) return false; u.pm = pm; u.pn = pn; return true; }
; template <class Epi, class Sched, bool STAMP = false>
; __device__ __forceinline__ void gemm_phase(PG8_LAS unsigned char* lds, const Gemm g, const Sched& S, const Epi& E, unsigned long long* stamps) {
;     int tid_ = threadIdx.x; asm volatile("" : "+v"(tid_)); const int tid = tid_, wid = __builtin_amdgcn_readfirstlane(tid >> 6), lane = tid & 63, wr = wid >> 2, wc = wid & 3, fr = lane & 15, fq = lane >> 4;
;     const int K = g.K, nt = K / BK, LD = g.ld;
;     unsigned voffA[2], voffB[2];
; #pragma unroll
;     for (int i = 0; i < 2; ++i) { int R, C; stage_rc(tid * 16 + i * 8192, R, C); const int Rb = Epi::PERM ? ((R & ~31) + perm32(R & 31)) : R;
;         voffA[i] = (unsigned)(R * LD + C) * 2u; voffB[i] = (unsigned)(Rb * LD + C) * 2u; }
;     const size_t kstep = (size_t)(BK * 2);
;     const size_t hstep = (size_t)HALF * LD * 2;
;     const size_t tstep = 2 * hstep;
;     const unsigned ldsw = (unsigned)wid * 1024u;
;     const int aoff = lds_byte(wr * 64 + fr, fq * 8), boff = lds_byte(wc * 32 + fr, fq * 8);
;     ...
;     Unit cur, nxt; int ui = 0;
;     if (!S.next(0, cur)) return;
;     f32x4 acc[2][2][4][2];
; #pragma unroll
;     for (int a = 0; a < 2; ++a)
; #pragma unroll
;         for (int b = 0; b < 2; ++b)
; #pragma unroll
;             for (int m = 0; m < 4; ++m)
; #pragma unroll
;                 for (int n = 0; n < 2; ++n) acc[a][b][m][n] = (f32x4){0.f, 0.f, 0.f, 0.f};
;     bf16x8 At[4][2], B0[2][2], B1[2][2];
;     const char* cA = (const char*)g.A + (size_t)cur.pm * tstep; const char* cB = (const char*)g.Bt + (size_t)cur.pn * tstep;
;     S.a_ready(cur);
;     PG8_STAGE(PG8_SB(0, 0), cB, voffB); PG8_STAGE(PG8_SA(0, 0), cA, voffA); PG8_STAGE(PG8_SB(0, 1), cB + hstep, voffB); PG8_STAGE(PG8_SA(0, 1), cA + hstep, voffA);
;     if (wr == 1) PG8_BAR;
; __global__ void __launch_bounds__(512, 2) mega_fwd(Params prm) {
;     ...
;         case 11: { GEMM_PRO; EpiResid E; E.X = p.out; E.XB = XB; E.rowss_out = rs_ffn; E.Xp0 = l == 0 ? INP(p, 0) : nullptr; E.Xs0 = l == 0 ? INP(p, 1) : nullptr;
;                    run_gemm(lds, (const bf16_t*)(ws + OFF_A), (const bf16_t*)(ws + OFF_WO), 1024, 1024, E, T_P);
.LBB0_129:
	s_add_u32 s60, s10, 0x5500000
	s_addc_u32 s61, s46, 0
	s_add_u32 s62, s10, 0xe00000
	s_addc_u32 s63, s46, 0
	s_and_b64 s[2:3], s[34:35], exec
	s_mov_b32 s2, 0x33000
	s_cselect_b32 s2, s2, 0x11000
	s_add_u32 s2, s10, s2
	s_addc_u32 s3, s46, 0
	s_add_u32 s2, s2, 0x2060000
	s_addc_u32 s3, s3, 0
	s_andn2_b64 vcc, exec, s[6:7]
	s_cbranch_vccnz .LBB0_209
	v_ashrrev_i32_e32 v1, 31, v9
	v_lshrrev_b32_e32 v1, 26, v1
	v_add_u32_e32 v1, v9, v1
	v_ashrrev_i32_e32 v8, 6, v1
	v_bfe_i32 v1, v9, 27, 1
	v_lshlrev_b32_e32 v0, 4, v9
	v_lshrrev_b32_e32 v1, 22, v1
	v_add_u32_e32 v1, v0, v1
	v_and_b32_e32 v1, 0xfffffc00, v1
	v_sub_u32_e32 v1, v0, v1
	v_lshrrev_b32_e32 v2, 4, v1
	v_bitop3_b32 v1, v2, v1, 32 bitop3:0x6c
	v_ashrrev_i32_e32 v3, 31, v1
	v_lshrrev_b32_e32 v3, 26, v3
	v_add_u32_e32 v3, v1, v3
	v_lshlrev_b32_e32 v2, 3, v8
	v_ashrrev_i32_e32 v10, 6, v3
	v_and_b32_e32 v3, 0xc0, v3
	v_and_b32_e32 v2, 0x1ffff0, v2
	v_lshlrev_b32_e32 v4, 5, v8
	v_sub_u32_e32 v1, v1, v3
	v_add_u32_e32 v2, v10, v2
	v_and_b32_e32 v11, 32, v4
	v_ashrrev_i16_sdwa v1, v188, sext(v1) dst_sel:DWORD dst_unused:UNUSED_PAD src0_sel:DWORD src1_sel:BYTE_0
	s_waitcnt lgkmcnt(0)
	v_bfe_i32 v12, v1, 0, 16
	v_lshl_or_b32 v1, v2, 10, v11
	v_add_u32_e32 v0, 0x2000, v0
	v_add_lshl_u32 v148, v1, v12, 1
	v_ashrrev_i32_e32 v1, 31, v0
	v_lshrrev_b32_e32 v1, 22, v1
	v_add_u32_e32 v1, v0, v1
	v_ashrrev_i32_e32 v13, 10, v1
	v_mul_i32_i24_e32 v1, 0x400, v13
	v_sub_u32_e32 v0, v0, v1
	v_lshrrev_b32_e32 v1, 4, v0
	v_bitop3_b32 v0, v1, v0, 32 bitop3:0x6c
	v_ashrrev_i32_e32 v2, 31, v0
	v_lshrrev_b32_e32 v2, 26, v2
	s_ashr_i32 s7, s53, 6
	s_ashr_i32 s31, s30, 31
	s_ashr_i32 s37, s36, 31
	s_ashr_i32 s6, s53, 8
	v_add_u32_e32 v2, v0, v2
	s_lshl_b32 s64, s7, 10
	s_lshl_b64 s[12:13], s[30:31], 19
	s_lshl_b64 s[14:15], s[36:37], 19
	v_lshlrev_b32_e32 v1, 3, v13
	v_ashrrev_i32_e32 v14, 6, v2
	v_and_b32_e32 v2, 0xc0, v2
	s_add_u32 s48, s62, s14
	v_and_b32_e32 v1, 0x1ffff0, v1
	v_lshlrev_b32_e32 v3, 5, v13
	v_sub_u32_e32 v0, v0, v2
	s_addc_u32 s49, s63, s15
	s_add_i32 s37, s64, 0
	v_add_u32_e32 v1, v14, v1
	v_and_b32_e32 v15, 32, v3
	v_ashrrev_i16_sdwa v0, v188, sext(v0) dst_sel:DWORD dst_unused:UNUSED_PAD src0_sel:DWORD src1_sel:BYTE_0
	s_add_i32 m0, s37, 0x10000
	v_bfe_i32 v16, v0, 0, 16
	v_lshl_or_b32 v0, v1, 10, v15
	global_load_lds_dwordx4 v148, s[48:49]
	s_add_i32 m0, s37, 0x12000
	v_add_lshl_u32 v150, v0, v16, 1
	s_add_u32 s44, s60, s12
	s_mov_b32 s75, s65
	global_load_lds_dwordx4 v150, s[48:49]
	s_addc_u32 s45, s61, s13
	s_mov_b32 m0, s37
	s_add_i32 s65, s37, 0x2000
	global_load_lds_dwordx4 v148, s[44:45]
	s_mov_b32 m0, s65
	s_add_u32 s12, s48, 0x40000
	global_load_lds_dwordx4 v150, s[44:45]
	s_addc_u32 s13, s49, 0
	s_add_i32 m0, s37, 0x14000
	v_mov_b32_e32 v149, v129
	global_load_lds_dwordx4 v148, s[12:13]
	s_add_i32 m0, s37, 0x16000
	v_mov_b32_e32 v151, v129
	global_load_lds_dwordx4 v150, s[12:13]
	s_add_u32 s12, s44, 0x40000
	s_addc_u32 s13, s45, 0
	s_add_i32 s76, s37, 0x4000
	s_mov_b32 m0, s76
	s_add_i32 s77, s37, 0x6000
	global_load_lds_dwordx4 v148, s[12:13]
	s_mov_b32 m0, s77
	v_lshl_add_u64 v[6:7], s[48:49], 0, v[148:149]
	global_load_lds_dwordx4 v150, s[12:13]
	v_lshl_add_u64 v[4:5], s[48:49], 0, v[150:151]
	v_lshl_add_u64 v[2:3], s[44:45], 0, v[148:149]
	s_cmp_lg_u32 s6, 1
	v_lshl_add_u64 v[0:1], s[44:45], 0, v[150:151]
	s_cbranch_scc1 .LBB0_132
	s_barrier
	s_setprio 1

; template <class Epi, class Sched, bool STAMP = false>
; __device__ __forceinline__ void gemm_phase(PG8_LAS unsigned char* lds, const Gemm g, const Sched& S, const Epi& E, unsigned long long* stamps) {
;     int tid_ = threadIdx.x; asm volatile("" : "+v"(tid_)); const int tid = tid_, wid = __builtin_amdgcn_readfirstlane(tid >> 6), lane = tid & 63, wr = wid >> 2, wc = wid & 3, fr = lane & 15, fq = lane >> 4;
;     const int K = g.K, nt = K / BK, LD = g.ld;
;     unsigned voffA[2], voffB[2];
; #pragma unroll
;     for (int i = 0; i < 2; ++i) { int R, C; stage_rc(tid * 16 + i * 8192, R, C); const int Rb = Epi::PERM ? ((R & ~31) + perm32(R & 31)) : R;
;         voffA[i] = (unsigned)(R * LD + C) * 2u; voffB[i] = (unsigned)(Rb * LD + C) * 2u; }
;     const size_t kstep = (size_t)(BK * 2);
;     const size_t hstep = (size_t)HALF * LD * 2;
;     const size_t tstep = 2 * hstep;
;     const unsigned ldsw = (unsigned)wid * 1024u;
;     const int aoff = lds_byte(wr * 64 + fr, fq * 8), boff = lds_byte(wc * 32 + fr, fq * 8);
;     ...
;     Unit cur, nxt; int ui = 0;
;     if (!S.next(0, cur)) return;
;     f32x4 acc[2][2][4][2];
; #pragma unroll
;     for (int a = 0; a < 2; ++a)
; #pragma unroll
;         for (int b = 0; b < 2; ++b)
; #pragma unroll
;             for (int m = 0; m < 4; ++m)
; #pragma unroll
;                 for (int n = 0; n < 2; ++n) acc[a][b][m][n] = (f32x4){0.f, 0.f, 0.f, 0.f};
;     bf16x8 At[4][2], B0[2][2], B1[2][2];
;     const char* cA = (const char*)g.A + (size_t)cur.pm * tstep; const char* cB = (const char*)g.Bt + (size_t)cur.pn * tstep;
;     S.a_ready(cur);
;     PG8_STAGE(PG8_SB(0, 0), cB, voffB); PG8_STAGE(PG8_SA(0, 0), cA, voffA); PG8_STAGE(PG8_SB(0, 1), cB + hstep, voffB); PG8_STAGE(PG8_SA(0, 1), cA + hstep, voffA);
;     if (wr == 1) PG8_BAR;
; __device__ __forceinline__ void run_wo_sample_tasks(LAS unsigned char* lds, unsigned char* ws) {
;     const int t = bidx(); OneUnit S; S.valid = t < 64; const int u = (t >> 2) & 15, sl = t & 3; S.pm = 64 + (u >> 2); S.pn = u & 3;
;     pg8::Gemm g; g.A = (const bf16_t*)(ws + OFF_A) + sl * 256; g.Bt = (const bf16_t*)(ws + OFF_WO) + sl * 256; g.M = T_ALL; g.N = 1024; g.K = 256; g.ld = 1024;
;     EpiPartial EA; EA.PART = (float*)(ws + OFF_GPART) + (size_t)sl * 1024 * 1024; EA.ldp = 1024;
;     pg8::gemm_phase<EpiPartial, OneUnit, false>(lds, g, S, EA, nullptr);
.LBB0_208:
	s_setprio 0
	s_barrier
.LBB0_209:
	s_mov_b32 s0, s90
	v_mov_b32_e32 v0, v184
	s_cmp_gt_i32 s0, 63
	s_nop 0
	v_readfirstlane_b32 s40, v0
	s_cbranch_scc1 .LBB0_217
	s_waitcnt lgkmcnt(0)
	v_lshlrev_b32_e32 v1, 4, v0
	v_add_u32_e32 v2, 0x2000, v1
	v_ashrrev_i32_e32 v3, 31, v2
	v_lshrrev_b32_e32 v3, 22, v3
	v_add_u32_e32 v3, v2, v3
	v_ashrrev_i32_e32 v3, 10, v3
	v_mul_i32_i24_e32 v4, 0x400, v3
	v_sub_u32_e32 v2, v2, v4
	v_lshrrev_b32_e32 v4, 4, v2
	v_bitop3_b32 v2, v4, v2, 32 bitop3:0x6c
	v_ashrrev_i32_e32 v4, 31, v2
	v_lshrrev_b32_e32 v4, 26, v4
	v_add_u32_e32 v4, v2, v4
	v_lshrrev_b32_e32 v5, 6, v4
	v_lshlrev_b32_e32 v6, 3, v3
	v_and_b32_e32 v4, 0xc0, v4
	v_and_b32_e32 v6, 0x1ffff0, v6
	v_lshlrev_b32_e32 v3, 5, v3
	v_sub_u32_e32 v2, v2, v4
	v_add_u32_e32 v5, v5, v6
	v_and_b32_e32 v3, 32, v3
	v_ashrrev_i16_sdwa v2, v188, sext(v2) dst_sel:DWORD dst_unused:UNUSED_PAD src0_sel:DWORD src1_sel:BYTE_0
	v_lshl_or_b32 v3, v5, 10, v3
	v_bfe_i32 v2, v2, 0, 16
	v_add_lshl_u32 v148, v3, v2, 1
	v_bfe_i32 v2, v0, 27, 1
	v_lshrrev_b32_e32 v2, 22, v2
	v_add_u32_e32 v2, v1, v2
	v_and_b32_e32 v2, 0xfffffc00, v2
	v_sub_u32_e32 v1, v1, v2
	v_lshrrev_b32_e32 v2, 4, v1
	s_and_b32 s43, s0, 3
	s_bfe_u32 s1, s0, 0x20004
	s_ashr_i32 s12, s40, 6
	v_bitop3_b32 v1, v2, v1, 32 bitop3:0x6c
	v_ashrrev_i32_e32 v4, 31, v0
	s_or_b32 s42, s1, 64
	s_bfe_u32 s41, s0, 0x20002
	s_ashr_i32 s13, s40, 8
	s_lshl_b32 s44, s12, 10
	s_lshl_b32 s0, s43, 9
	v_ashrrev_i32_e32 v2, 31, v1
	v_lshrrev_b32_e32 v4, 26, v4
	s_add_u32 s1, s62, s0
	v_lshrrev_b32_e32 v2, 26, v2
	v_add_u32_e32 v4, v0, v4
	s_addc_u32 s4, s63, 0
	v_add_u32_e32 v2, v1, v2
	v_ashrrev_i32_e32 v4, 6, v4
	s_add_u32 s5, s60, s0
	v_lshrrev_b32_e32 v3, 6, v2
	v_lshlrev_b32_e32 v5, 3, v4
	v_and_b32_e32 v2, 0xc0, v2
	s_addc_u32 s6, s61, 0
	v_and_b32_e32 v5, 0x1ffff0, v5
	v_lshlrev_b32_e32 v4, 5, v4
	v_sub_u32_e32 v1, v1, v2
	s_lshl_b32 s7, s42, 19
	s_lshl_b32 s0, s41, 19
	v_add_u32_e32 v3, v3, v5
	v_and_b32_e32 v4, 32, v4
	v_ashrrev_i16_sdwa v1, v188, sext(v1) dst_sel:DWORD dst_unused:UNUSED_PAD src0_sel:DWORD src1_sel:BYTE_0
	s_add_u32 s0, s1, s0
	v_lshl_or_b32 v3, v3, 10, v4
	v_bfe_i32 v1, v1, 0, 16
	s_addc_u32 s1, s4, 0
	s_add_i32 s45, s44, 0
	v_add_lshl_u32 v128, v3, v1, 1
	s_add_i32 m0, s45, 0x10000
	s_mov_b32 s64, s65
	global_load_lds_dwordx4 v128, s[0:1]
	s_add_i32 m0, s45, 0x12000
	s_add_u32 s4, s5, s7
	global_load_lds_dwordx4 v148, s[0:1]
	s_addc_u32 s5, s6, 0
	s_mov_b32 m0, s45
	s_add_i32 s47, s45, 0x2000
	global_load_lds_dwordx4 v128, s[4:5]
	s_mov_b32 m0, s47
	s_add_u32 s6, s0, 0x40000
	global_load_lds_dwordx4 v148, s[4:5]
	s_addc_u32 s7, s1, 0
	s_add_i32 m0, s45, 0x14000
	s_nop 0
	global_load_lds_dwordx4 v128, s[6:7]
	s_add_i32 m0, s45, 0x16000
	s_nop 0
	global_load_lds_dwordx4 v148, s[6:7]
	s_add_u32 s6, s4, 0x40000
	s_addc_u32 s7, s5, 0
	s_add_i32 s48, s45, 0x4000
	s_mov_b32 m0, s48
	s_add_i32 s49, s45, 0x6000
	global_load_lds_dwordx4 v128, s[6:7]
	s_mov_b32 m0, s49
	s_cmp_lg_u32 s13, 1
	global_load_lds_dwordx4 v148, s[6:7]
	s_cbranch_scc1 .LBB0_212
	s_barrier
	s_setprio 1

; #define PG8_WAIT_V(n) asm volatile("s_waitcnt vmcnt(" #n ")" ::: "memory")
; #define PG8_BAR __builtin_amdgcn_s_barrier()
; template <class Epi, class Sched, bool STAMP = false>
; __device__ __forceinline__ void gemm_phase(PG8_LAS unsigned char* lds, const Gemm g, const Sched& S, const Epi& E, unsigned long long* stamps) {
;     ...
;     PG8_WAIT_V(0);
;     if (wr == 0) PG8_BAR;
;     PG8_BAR;
.LBB0_216:
	s_setprio 0
	v_readlane_b32 s52, v242, 26
	v_readlane_b32 s29, v242, 27
	v_readlane_b32 s39, v242, 28
	s_mov_b32 s38, 0x1ffff
	s_mov_b32 s65, s64
	s_barrier

; #define PG8_STAGE(bufoff, gbase, voff) do { _Pragma("unroll") for (int _i = 0; _i < 2; ++_i) \
;         __builtin_amdgcn_global_load_lds((const unsigned*)((const char*)(gbase) + (voff)[_i]), (PG8_LAS unsigned*)(lds + (bufoff) + ldsw + _i * 8192), 16, 0, 0); } while (0)
; #define PG8_BAR __builtin_amdgcn_s_barrier()
; template <class Epi, class Sched, bool STAMP = false>
; __device__ __forceinline__ void gemm_phase(PG8_LAS unsigned char* lds, const Gemm g, const Sched& S, const Epi& E, unsigned long long* stamps) {
;     int tid_ = threadIdx.x; asm volatile("" : "+v"(tid_)); const int tid = tid_, wid = __builtin_amdgcn_readfirstlane(tid >> 6), lane = tid & 63, wr = wid >> 2, wc = wid & 3, fr = lane & 15, fq = lane >> 4;
;     const int K = g.K, nt = K / BK, LD = g.ld;
;     unsigned voffA[2], voffB[2];
; #pragma unroll
;     for (int i = 0; i < 2; ++i) { int R, C; stage_rc(tid * 16 + i * 8192, R, C); const int Rb = Epi::PERM ? ((R & ~31) + perm32(R & 31)) : R;
;         voffA[i] = (unsigned)(R * LD + C) * 2u; voffB[i] = (unsigned)(Rb * LD + C) * 2u; }
;     const size_t kstep = (size_t)(BK * 2);
;     const size_t hstep = (size_t)HALF * LD * 2;
;     const size_t tstep = 2 * hstep;
;     const unsigned ldsw = (unsigned)wid * 1024u;
;     const int aoff = lds_byte(wr * 64 + fr, fq * 8), boff = lds_byte(wc * 32 + fr, fq * 8);
;     ...
;     Unit cur, nxt; int ui = 0;
;     if (!S.next(0, cur)) return;
;     f32x4 acc[2][2][4][2];
; #pragma unroll
;     for (int a = 0; a < 2; ++a)
; #pragma unroll
;         for (int b = 0; b < 2; ++b)
; #pragma unroll
;             for (int m = 0; m < 4; ++m)
; #pragma unroll
;                 for (int n = 0; n < 2; ++n) acc[a][b][m][n] = (f32x4){0.f, 0.f, 0.f, 0.f};
;     bf16x8 At[4][2], B0[2][2], B1[2][2];
;     const char* cA = (const char*)g.A + (size_t)cur.pm * tstep; const char* cB = (const char*)g.Bt + (size_t)cur.pn * tstep;
;     S.a_ready(cur);
;     PG8_STAGE(PG8_SB(0, 0), cB, voffB); PG8_STAGE(PG8_SA(0, 0), cA, voffA); PG8_STAGE(PG8_SB(0, 1), cB + hstep, voffB); PG8_STAGE(PG8_SA(0, 1), cA + hstep, voffA);
;     if (wr == 1) PG8_BAR;
; __global__ void __launch_bounds__(512, 2) mega_fwd(Params prm) {
;     ...
;             { EpiBf<2> E; E.O = TA; E.ldc = 1024; E.rowss = nullptr; run_gemm(lds, (const bf16_t*)(ws + OFF_B), (const bf16_t*)(ws + OFF_WOA), 1024, 512, E, T_P); }
.LBB0_283:
	v_bfe_i32 v1, v6, 27, 1
	v_lshlrev_b32_e32 v3, 4, v6
	v_lshrrev_b32_e32 v1, 22, v1
	v_ashrrev_i32_e32 v0, 31, v6
	v_add_u32_e32 v1, v3, v1
	v_lshrrev_b32_e32 v0, 26, v0
	v_and_b32_e32 v1, 0xfffffc00, v1
	v_add_u32_e32 v0, v6, v0
	v_sub_u32_e32 v1, v3, v1
	v_ashrrev_i32_e32 v0, 6, v0
	v_lshrrev_b32_e32 v2, 4, v1
	v_bitop3_b32 v2, v2, v1, 32 bitop3:0x6c
	v_lshlrev_b32_e32 v1, 3, v0
	v_and_b32_e32 v4, -16, v1
	v_ashrrev_i32_e32 v1, 31, v2
	v_lshrrev_b32_e32 v1, 26, v1
	s_waitcnt lgkmcnt(0)
	v_add_u32_e32 v5, v2, v1
	v_ashrrev_i32_e32 v1, 6, v5
	v_and_b32_e32 v5, 0xc0, v5
	v_sub_u32_e32 v2, v2, v5
	v_lshlrev_b32_e32 v7, 5, v0
	v_ashrrev_i16_sdwa v2, v188, sext(v2) dst_sel:DWORD dst_unused:UNUSED_PAD src0_sel:DWORD src1_sel:BYTE_0
	v_and_b32_e32 v7, 32, v7
	v_bfe_i32 v2, v2, 0, 16
	v_add_u32_e32 v4, v1, v4
	v_and_b32_e32 v9, 3, v1
	s_mov_b32 s3, 0x3fffe0
	v_add_lshl_u32 v7, v7, v2, 1
	v_lshlrev_b32_e32 v5, 1, v4
	v_lshrrev_b32_e32 v8, 2, v4
	v_and_or_b32 v9, v4, s3, v9
	v_lshl_add_u32 v148, v4, 10, v7
	v_add_u32_e32 v4, 0x2000, v3
	v_ashrrev_i32_e32 v3, 31, v4
	v_lshrrev_b32_e32 v3, 22, v3
	v_and_b32_e32 v5, 24, v5
	v_and_b32_e32 v8, 4, v8
	v_add_u32_e32 v3, v4, v3
	v_or3_b32 v5, v9, v8, v5
	v_ashrrev_i32_e32 v3, 10, v3
	v_lshl_add_u32 v128, v5, 10, v7
	v_mul_i32_i24_e32 v5, 0x400, v3
	v_sub_u32_e32 v4, v4, v5
	v_lshrrev_b32_e32 v5, 4, v4
	v_bitop3_b32 v5, v5, v4, 32 bitop3:0x6c
	v_lshlrev_b32_e32 v4, 3, v3
	v_and_b32_e32 v7, -16, v4
	v_ashrrev_i32_e32 v4, 31, v5
	v_lshrrev_b32_e32 v4, 26, v4
	v_add_u32_e32 v8, v5, v4
	v_ashrrev_i32_e32 v4, 6, v8
	v_add_u32_e32 v7, v4, v7
	v_and_b32_e32 v11, 3, v4
	s_add_i32 s2, s4, s2
	v_and_or_b32 v11, v7, s3, v11
	s_ashr_i32 s3, s2, 31
	s_lshr_b32 s3, s3, 27
	s_add_i32 s3, s2, s3
	s_ashr_i32 s4, s3, 5
	s_and_b32 s3, s3, 0xffe0
	s_sub_i32 s2, s2, s3
	s_bfe_i32 s3, s2, 0x80000
	s_bfe_u32 s3, s3, 0x3000c
	s_add_i32 s3, s2, s3
	s_lshl_b32 s7, s4, 3
	s_bfe_i32 s4, s3, 0x80000
	s_and_b32 s3, s3, 0xf8
	s_sub_i32 s2, s2, s3
	s_sext_i32_i16 s4, s4
	s_sext_i32_i8 s2, s2
	s_ashr_i32 s5, s36, 8
	s_lshr_b32 s4, s4, 3
	s_add_i32 s2, s7, s2
	s_ashr_i32 s6, s36, 6
	s_ashr_i32 s3, s2, 31
	s_bfe_i64 s[14:15], s[4:5], 0x100000
	v_and_b32_e32 v8, 0xc0, v8
	s_lshl_b32 s40, s6, 10
	s_lshl_b64 s[12:13], s[2:3], 18
	s_lshl_b64 s[14:15], s[14:15], 18
	v_sub_u32_e32 v5, v5, v8
	s_add_u32 s26, s44, s14
	v_lshlrev_b32_e32 v9, 5, v3
	v_ashrrev_i16_sdwa v5, v188, sext(v5) dst_sel:DWORD dst_unused:UNUSED_PAD src0_sel:DWORD src1_sel:BYTE_0
	v_lshlrev_b32_e32 v8, 1, v7
	v_lshrrev_b32_e32 v10, 2, v7
	s_addc_u32 s27, s45, s15
	s_add_i32 s3, s40, 0
	v_and_b32_e32 v9, 32, v9
	v_bfe_i32 v5, v5, 0, 16
	v_and_b32_e32 v8, 24, v8
	v_and_b32_e32 v10, 4, v10
	s_add_i32 m0, s3, 0x10000
	v_or3_b32 v8, v11, v10, v8
	v_add_lshl_u32 v9, v9, v5, 1
	global_load_lds_dwordx4 v128, s[26:27]
	s_add_i32 m0, s3, 0x12000
	v_lshl_add_u32 v152, v8, 10, v9
	s_add_u32 s24, s20, s12
	global_load_lds_dwordx4 v152, s[26:27]
	s_addc_u32 s25, s21, s13
	s_mov_b32 m0, s3
	s_add_i32 s41, s3, 0x2000
	v_lshl_add_u32 v150, v7, 10, v9
	global_load_lds_dwordx4 v148, s[24:25]
	s_mov_b32 m0, s41
	s_add_u32 s12, s26, 0x20000
	global_load_lds_dwordx4 v150, s[24:25]
	s_addc_u32 s13, s27, 0
	s_add_i32 m0, s3, 0x14000
	s_nop 0
	global_load_lds_dwordx4 v128, s[12:13]
	s_add_i32 m0, s3, 0x16000
	s_nop 0
	global_load_lds_dwordx4 v152, s[12:13]
	s_add_u32 s12, s24, 0x20000
	s_addc_u32 s13, s25, 0
	s_add_i32 s42, s3, 0x4000
	s_mov_b32 m0, s42
	s_add_i32 s43, s3, 0x6000
	global_load_lds_dwordx4 v148, s[12:13]
	s_mov_b32 m0, s43
	s_cmp_lg_u32 s5, 1
	global_load_lds_dwordx4 v150, s[12:13]
	s_cbranch_scc1 .LBB0_285
	s_barrier
	s_setprio 1

; #define PG8_WAIT_V(n) asm volatile("s_waitcnt vmcnt(" #n ")" ::: "memory")
; #define PG8_BAR __builtin_amdgcn_s_barrier()
; template <class Epi, class Sched, bool STAMP = false>
; __device__ __forceinline__ void gemm_phase(PG8_LAS unsigned char* lds, const Gemm g, const Sched& S, const Epi& E, unsigned long long* stamps) {
;     ...
;     PG8_WAIT_V(0);
;     if (wr == 0) PG8_BAR;
;     PG8_BAR;
.LBB0_297:
	s_setprio 0
	s_mov_b32 s65, s60
	s_barrier

; #define PG8_STAGE(bufoff, gbase, voff) do { _Pragma("unroll") for (int _i = 0; _i < 2; ++_i) \
;         __builtin_amdgcn_global_load_lds((const unsigned*)((const char*)(gbase) + (voff)[_i]), (PG8_LAS unsigned*)(lds + (bufoff) + ldsw + _i * 8192), 16, 0, 0); } while (0)
; #define PG8_BAR __builtin_amdgcn_s_barrier()
; template <class Epi, class Sched, bool STAMP = false>
; __device__ __forceinline__ void gemm_phase(PG8_LAS unsigned char* lds, const Gemm g, const Sched& S, const Epi& E, unsigned long long* stamps) {
;     int tid_ = threadIdx.x; asm volatile("" : "+v"(tid_)); const int tid = tid_, wid = __builtin_amdgcn_readfirstlane(tid >> 6), lane = tid & 63, wr = wid >> 2, wc = wid & 3, fr = lane & 15, fq = lane >> 4;
;     const int K = g.K, nt = K / BK, LD = g.ld;
;     unsigned voffA[2], voffB[2];
; #pragma unroll
;     for (int i = 0; i < 2; ++i) { int R, C; stage_rc(tid * 16 + i * 8192, R, C); const int Rb = Epi::PERM ? ((R & ~31) + perm32(R & 31)) : R;
;         voffA[i] = (unsigned)(R * LD + C) * 2u; voffB[i] = (unsigned)(Rb * LD + C) * 2u; }
;     const size_t kstep = (size_t)(BK * 2);
;     const size_t hstep = (size_t)HALF * LD * 2;
;     const size_t tstep = 2 * hstep;
;     const unsigned ldsw = (unsigned)wid * 1024u;
;     const int aoff = lds_byte(wr * 64 + fr, fq * 8), boff = lds_byte(wc * 32 + fr, fq * 8);
;     ...
;     Unit cur, nxt; int ui = 0;
;     if (!S.next(0, cur)) return;
;     f32x4 acc[2][2][4][2];
; #pragma unroll
;     for (int a = 0; a < 2; ++a)
; #pragma unroll
;         for (int b = 0; b < 2; ++b)
; #pragma unroll
;             for (int m = 0; m < 4; ++m)
; #pragma unroll
;                 for (int n = 0; n < 2; ++n) acc[a][b][m][n] = (f32x4){0.f, 0.f, 0.f, 0.f};
;     bf16x8 At[4][2], B0[2][2], B1[2][2];
;     const char* cA = (const char*)g.A + (size_t)cur.pm * tstep; const char* cB = (const char*)g.Bt + (size_t)cur.pn * tstep;
;     S.a_ready(cur);
;     PG8_STAGE(PG8_SB(0, 0), cB, voffB); PG8_STAGE(PG8_SA(0, 0), cA, voffA); PG8_STAGE(PG8_SB(0, 1), cB + hstep, voffB); PG8_STAGE(PG8_SA(0, 1), cA + hstep, voffA);
;     if (wr == 1) PG8_BAR;
; __global__ void __launch_bounds__(512, 2) mega_fwd(Params prm) {
;     ...
;             { EpiGate<0> E; E.M = TA; E.Tm = TA; E.rowss = rs_mix; run_gemm(lds, XB, (const bf16_t*)(ws + OFF_WGA), 1024, 1024, E, T_P); }
.LBB0_303:
	v_bfe_i32 v1, v6, 27, 1
	v_lshlrev_b32_e32 v3, 4, v6
	v_lshrrev_b32_e32 v1, 22, v1
	v_ashrrev_i32_e32 v0, 31, v6
	v_add_u32_e32 v1, v3, v1
	v_lshrrev_b32_e32 v0, 26, v0
	v_and_b32_e32 v1, 0xfffffc00, v1
	v_add_u32_e32 v0, v6, v0
	v_sub_u32_e32 v1, v3, v1
	v_ashrrev_i32_e32 v0, 6, v0
	v_lshrrev_b32_e32 v2, 4, v1
	v_bitop3_b32 v2, v2, v1, 32 bitop3:0x6c
	v_lshlrev_b32_e32 v1, 3, v0
	v_and_b32_e32 v4, -16, v1
	v_ashrrev_i32_e32 v1, 31, v2
	v_lshrrev_b32_e32 v1, 26, v1
	s_waitcnt lgkmcnt(0)
	v_add_u32_e32 v5, v2, v1
	v_ashrrev_i32_e32 v1, 6, v5
	v_and_b32_e32 v5, 0xc0, v5
	v_sub_u32_e32 v2, v2, v5
	v_lshlrev_b32_e32 v7, 5, v0
	v_ashrrev_i16_sdwa v2, v188, sext(v2) dst_sel:DWORD dst_unused:UNUSED_PAD src0_sel:DWORD src1_sel:BYTE_0
	v_and_b32_e32 v7, 32, v7
	v_bfe_i32 v2, v2, 0, 16
	v_add_u32_e32 v4, v1, v4
	v_and_b32_e32 v9, 3, v1
	s_mov_b32 s3, 0x1fffe0
	v_add_lshl_u32 v7, v7, v2, 1
	v_lshlrev_b32_e32 v5, 1, v4
	v_lshrrev_b32_e32 v8, 2, v4
	v_and_or_b32 v9, v4, s3, v9
	v_lshl_add_u32 v148, v4, 11, v7
	v_add_u32_e32 v4, 0x2000, v3
	v_ashrrev_i32_e32 v3, 31, v4
	v_lshrrev_b32_e32 v3, 22, v3
	v_and_b32_e32 v5, 24, v5
	v_and_b32_e32 v8, 4, v8
	v_add_u32_e32 v3, v4, v3
	v_or3_b32 v5, v9, v8, v5
	v_ashrrev_i32_e32 v3, 10, v3
	v_lshl_add_u32 v128, v5, 11, v7
	v_mul_i32_i24_e32 v5, 0x400, v3
	v_sub_u32_e32 v4, v4, v5
	v_lshrrev_b32_e32 v5, 4, v4
	v_bitop3_b32 v5, v5, v4, 32 bitop3:0x6c
	v_lshlrev_b32_e32 v4, 3, v3
	v_and_b32_e32 v7, -16, v4
	v_ashrrev_i32_e32 v4, 31, v5
	v_lshrrev_b32_e32 v4, 26, v4
	v_add_u32_e32 v8, v5, v4
	v_ashrrev_i32_e32 v4, 6, v8
	v_add_u32_e32 v7, v4, v7
	v_and_b32_e32 v11, 3, v4
	s_add_i32 s2, s4, s2
	v_and_or_b32 v11, v7, s3, v11
	s_ashr_i32 s3, s2, 31
	s_lshr_b32 s3, s3, 27
	s_add_i32 s3, s2, s3
	s_ashr_i32 s4, s3, 5
	s_and_b32 s3, s3, 0xffe0
	s_sub_i32 s2, s2, s3
	s_bfe_i32 s3, s2, 0x80000
	s_bfe_u32 s3, s3, 0x3000c
	s_add_i32 s3, s2, s3
	s_bfe_i32 s5, s3, 0x80000
	s_and_b32 s3, s3, 0xf8
	s_sub_i32 s2, s2, s3
	s_lshl_b32 s4, s4, 3
	s_sext_i32_i16 s5, s5
	s_sext_i32_i8 s2, s2
	s_ashr_i32 s7, s36, 8
	s_lshr_b32 s6, s5, 3
	s_add_i32 s2, s4, s2
	s_ashr_i32 s14, s36, 6
	s_ashr_i32 s3, s2, 31
	s_bfe_i64 s[12:13], s[6:7], 0x100000
	v_and_b32_e32 v8, 0xc0, v8
	s_lshl_b32 s56, s14, 10
	s_lshl_b64 s[4:5], s[2:3], 19
	s_lshl_b64 s[12:13], s[12:13], 19
	v_sub_u32_e32 v5, v5, v8
	s_add_u32 s12, s22, s12
	v_lshlrev_b32_e32 v9, 5, v3
	v_ashrrev_i16_sdwa v5, v188, sext(v5) dst_sel:DWORD dst_unused:UNUSED_PAD src0_sel:DWORD src1_sel:BYTE_0
	v_lshlrev_b32_e32 v8, 1, v7
	v_lshrrev_b32_e32 v10, 2, v7
	s_addc_u32 s13, s23, s13
	s_add_i32 s3, s56, 0
	v_and_b32_e32 v9, 32, v9
	v_bfe_i32 v5, v5, 0, 16
	v_and_b32_e32 v8, 24, v8
	v_and_b32_e32 v10, 4, v10
	s_add_i32 m0, s3, 0x10000
	v_or3_b32 v8, v11, v10, v8
	v_add_lshl_u32 v9, v9, v5, 1
	global_load_lds_dwordx4 v128, s[12:13]
	s_add_i32 m0, s3, 0x12000
	v_lshl_add_u32 v152, v8, 11, v9
	s_add_u32 s4, s42, s4
	global_load_lds_dwordx4 v152, s[12:13]
	s_addc_u32 s5, s43, s5
	s_mov_b32 m0, s3
	s_add_i32 s57, s3, 0x2000
	v_lshl_add_u32 v150, v7, 11, v9
	global_load_lds_dwordx4 v148, s[4:5]
	s_mov_b32 m0, s57
	s_add_u32 s16, s12, 0x40000
	global_load_lds_dwordx4 v150, s[4:5]
	s_addc_u32 s17, s13, 0
	s_add_i32 m0, s3, 0x14000
	s_nop 0
	global_load_lds_dwordx4 v128, s[16:17]
	s_add_i32 m0, s3, 0x16000
	s_nop 0
	global_load_lds_dwordx4 v152, s[16:17]
	s_add_u32 s16, s4, 0x40000
	s_addc_u32 s17, s5, 0
	s_add_i32 s58, s3, 0x4000
	s_mov_b32 m0, s58
	s_add_i32 s59, s3, 0x6000
	global_load_lds_dwordx4 v148, s[16:17]
	s_mov_b32 m0, s59
	s_cmp_lg_u32 s7, 1
	global_load_lds_dwordx4 v150, s[16:17]
	s_cbranch_scc1 .LBB0_305
	s_barrier
	s_setprio 1

; #define PG8_WAIT_V(n) asm volatile("s_waitcnt vmcnt(" #n ")" ::: "memory")
; #define PG8_BAR __builtin_amdgcn_s_barrier()
; template <class Epi, class Sched, bool STAMP = false>
; __device__ __forceinline__ void gemm_phase(PG8_LAS unsigned char* lds, const Gemm g, const Sched& S, const Epi& E, unsigned long long* stamps) {
;     ...
;     PG8_WAIT_V(0);
;     if (wr == 0) PG8_BAR;
;     PG8_BAR;
.LBB0_317:
	s_setprio 0
	s_movk_i32 s58, 0xff60
	s_barrier

; #define PG8_STAGE(bufoff, gbase, voff) do { _Pragma("unroll") for (int _i = 0; _i < 2; ++_i) \
;         __builtin_amdgcn_global_load_lds((const unsigned*)((const char*)(gbase) + (voff)[_i]), (PG8_LAS unsigned*)(lds + (bufoff) + ldsw + _i * 8192), 16, 0, 0); } while (0)
; #define PG8_BAR __builtin_amdgcn_s_barrier()
; template <class Epi, class Sched, bool STAMP = false>
; __device__ __forceinline__ void gemm_phase(PG8_LAS unsigned char* lds, const Gemm g, const Sched& S, const Epi& E, unsigned long long* stamps) {
;     int tid_ = threadIdx.x; asm volatile("" : "+v"(tid_)); const int tid = tid_, wid = __builtin_amdgcn_readfirstlane(tid >> 6), lane = tid & 63, wr = wid >> 2, wc = wid & 3, fr = lane & 15, fq = lane >> 4;
;     const int K = g.K, nt = K / BK, LD = g.ld;
;     unsigned voffA[2], voffB[2];
; #pragma unroll
;     for (int i = 0; i < 2; ++i) { int R, C; stage_rc(tid * 16 + i * 8192, R, C); const int Rb = Epi::PERM ? ((R & ~31) + perm32(R & 31)) : R;
;         voffA[i] = (unsigned)(R * LD + C) * 2u; voffB[i] = (unsigned)(Rb * LD + C) * 2u; }
;     const size_t kstep = (size_t)(BK * 2);
;     const size_t hstep = (size_t)HALF * LD * 2;
;     const size_t tstep = 2 * hstep;
;     const unsigned ldsw = (unsigned)wid * 1024u;
;     const int aoff = lds_byte(wr * 64 + fr, fq * 8), boff = lds_byte(wc * 32 + fr, fq * 8);
;     ...
;     Unit cur, nxt; int ui = 0;
;     if (!S.next(0, cur)) return;
;     f32x4 acc[2][2][4][2];
; #pragma unroll
;     for (int a = 0; a < 2; ++a)
; #pragma unroll
;         for (int b = 0; b < 2; ++b)
; #pragma unroll
;             for (int m = 0; m < 4; ++m)
; #pragma unroll
;                 for (int n = 0; n < 2; ++n) acc[a][b][m][n] = (f32x4){0.f, 0.f, 0.f, 0.f};
;     bf16x8 At[4][2], B0[2][2], B1[2][2];
;     const char* cA = (const char*)g.A + (size_t)cur.pm * tstep; const char* cB = (const char*)g.Bt + (size_t)cur.pn * tstep;
;     S.a_ready(cur);
;     PG8_STAGE(PG8_SB(0, 0), cB, voffB); PG8_STAGE(PG8_SA(0, 0), cA, voffA); PG8_STAGE(PG8_SB(0, 1), cB + hstep, voffB); PG8_STAGE(PG8_SA(0, 1), cA + hstep, voffA);
;     if (wr == 1) PG8_BAR;
; __global__ void __launch_bounds__(512, 2) mega_fwd(Params prm) {
;     ...
;             { EpiBf<2> E; E.O = TB; E.ldc = 1024; E.rowss = nullptr; run_gemm(lds, (const bf16_t*)(ws + OFF_B + SLOT), (const bf16_t*)(ws + OFF_WOB), 1024, 512, E, T_P); }
.LBB0_323:
	v_bfe_i32 v1, v6, 27, 1
	v_lshlrev_b32_e32 v3, 4, v6
	v_lshrrev_b32_e32 v1, 22, v1
	v_ashrrev_i32_e32 v0, 31, v6
	v_add_u32_e32 v1, v3, v1
	v_lshrrev_b32_e32 v0, 26, v0
	v_and_b32_e32 v1, 0xfffffc00, v1
	v_add_u32_e32 v0, v6, v0
	v_sub_u32_e32 v1, v3, v1
	v_ashrrev_i32_e32 v0, 6, v0
	v_lshrrev_b32_e32 v2, 4, v1
	v_bitop3_b32 v2, v2, v1, 32 bitop3:0x6c
	v_lshlrev_b32_e32 v1, 3, v0
	v_and_b32_e32 v4, -16, v1
	v_ashrrev_i32_e32 v1, 31, v2
	v_lshrrev_b32_e32 v1, 26, v1
	s_waitcnt lgkmcnt(0)
	v_add_u32_e32 v5, v2, v1
	v_ashrrev_i32_e32 v1, 6, v5
	v_and_b32_e32 v5, 0xc0, v5
	v_sub_u32_e32 v2, v2, v5
	v_lshlrev_b32_e32 v7, 5, v0
	v_ashrrev_i16_sdwa v2, v188, sext(v2) dst_sel:DWORD dst_unused:UNUSED_PAD src0_sel:DWORD src1_sel:BYTE_0
	v_and_b32_e32 v7, 32, v7
	v_bfe_i32 v2, v2, 0, 16
	v_add_u32_e32 v4, v1, v4
	v_and_b32_e32 v9, 3, v1
	s_mov_b32 s3, 0x3fffe0
	v_add_lshl_u32 v7, v7, v2, 1
	v_lshlrev_b32_e32 v5, 1, v4
	v_lshrrev_b32_e32 v8, 2, v4
	v_and_or_b32 v9, v4, s3, v9
	v_lshl_add_u32 v148, v4, 10, v7
	v_add_u32_e32 v4, 0x2000, v3
	v_ashrrev_i32_e32 v3, 31, v4
	v_lshrrev_b32_e32 v3, 22, v3
	v_and_b32_e32 v5, 24, v5
	v_and_b32_e32 v8, 4, v8
	v_add_u32_e32 v3, v4, v3
	v_or3_b32 v5, v9, v8, v5
	v_ashrrev_i32_e32 v3, 10, v3
	v_lshl_add_u32 v128, v5, 10, v7
	v_mul_i32_i24_e32 v5, 0x400, v3
	v_sub_u32_e32 v4, v4, v5
	v_lshrrev_b32_e32 v5, 4, v4
	v_bitop3_b32 v5, v5, v4, 32 bitop3:0x6c
	v_lshlrev_b32_e32 v4, 3, v3
	v_and_b32_e32 v7, -16, v4
	v_ashrrev_i32_e32 v4, 31, v5
	v_lshrrev_b32_e32 v4, 26, v4
	v_add_u32_e32 v8, v5, v4
	v_ashrrev_i32_e32 v4, 6, v8
	v_add_u32_e32 v7, v4, v7
	v_and_b32_e32 v11, 3, v4
	s_add_i32 s2, s4, s2
	v_and_or_b32 v11, v7, s3, v11
	s_ashr_i32 s3, s2, 31
	s_lshr_b32 s3, s3, 27
	s_add_i32 s3, s2, s3
	s_ashr_i32 s4, s3, 5
	s_and_b32 s3, s3, 0xffe0
	s_sub_i32 s2, s2, s3
	s_bfe_i32 s3, s2, 0x80000
	s_bfe_u32 s3, s3, 0x3000c
	s_add_i32 s3, s2, s3
	s_lshl_b32 s13, s4, 3
	s_bfe_i32 s4, s3, 0x80000
	s_and_b32 s3, s3, 0xf8
	s_sub_i32 s2, s2, s3
	s_sext_i32_i16 s4, s4
	s_sext_i32_i8 s2, s2
	s_ashr_i32 s5, s46, 8
	s_lshr_b32 s4, s4, 3
	s_add_i32 s2, s13, s2
	s_ashr_i32 s12, s46, 6
	s_ashr_i32 s3, s2, 31
	s_bfe_i64 s[16:17], s[4:5], 0x100000
	v_and_b32_e32 v8, 0xc0, v8
	s_lshl_b32 s53, s12, 10
	s_lshl_b64 s[14:15], s[2:3], 18
	s_lshl_b64 s[16:17], s[16:17], 18
	v_sub_u32_e32 v5, v5, v8
	s_add_u32 s56, s6, s16
	v_lshlrev_b32_e32 v9, 5, v3
	v_ashrrev_i16_sdwa v5, v188, sext(v5) dst_sel:DWORD dst_unused:UNUSED_PAD src0_sel:DWORD src1_sel:BYTE_0
	v_lshlrev_b32_e32 v8, 1, v7
	v_lshrrev_b32_e32 v10, 2, v7
	s_addc_u32 s57, s7, s17
	s_add_i32 s3, s53, 0
	v_and_b32_e32 v9, 32, v9
	v_bfe_i32 v5, v5, 0, 16
	v_and_b32_e32 v8, 24, v8
	v_and_b32_e32 v10, 4, v10
	s_add_i32 m0, s3, 0x10000
	v_or3_b32 v8, v11, v10, v8
	v_add_lshl_u32 v9, v9, v5, 1
	global_load_lds_dwordx4 v128, s[56:57]
	s_add_i32 m0, s3, 0x12000
	v_lshl_add_u32 v152, v8, 10, v9
	s_add_u32 s36, s48, s14
	global_load_lds_dwordx4 v152, s[56:57]
	s_addc_u32 s37, s49, s15
	s_mov_b32 m0, s3
	s_add_i32 s60, s3, 0x2000
	v_lshl_add_u32 v150, v7, 10, v9
	global_load_lds_dwordx4 v148, s[36:37]
	s_mov_b32 m0, s60
	s_add_u32 s14, s56, 0x20000
	global_load_lds_dwordx4 v150, s[36:37]
	s_addc_u32 s15, s57, 0
	s_add_i32 m0, s3, 0x14000
	s_nop 0
	global_load_lds_dwordx4 v128, s[14:15]
	s_add_i32 m0, s3, 0x16000
	s_nop 0
	global_load_lds_dwordx4 v152, s[14:15]
	s_add_u32 s14, s36, 0x20000
	s_addc_u32 s15, s37, 0
	s_add_i32 s61, s3, 0x4000
	s_mov_b32 m0, s61
	s_add_i32 s62, s3, 0x6000
	global_load_lds_dwordx4 v148, s[14:15]
	s_mov_b32 m0, s62
	s_cmp_lg_u32 s5, 1
	global_load_lds_dwordx4 v150, s[14:15]
	s_cbranch_scc1 .LBB0_325
	s_barrier
	s_setprio 1

; #define PG8_WAIT_V(n) asm volatile("s_waitcnt vmcnt(" #n ")" ::: "memory")
; #define PG8_BAR __builtin_amdgcn_s_barrier()
; template <class Epi, class Sched, bool STAMP = false>
; __device__ __forceinline__ void gemm_phase(PG8_LAS unsigned char* lds, const Gemm g, const Sched& S, const Epi& E, unsigned long long* stamps) {
;     ...
;     PG8_WAIT_V(0);
;     if (wr == 0) PG8_BAR;
;     PG8_BAR;
.LBB0_337:
	s_setprio 0
	s_mov_b32 s62, 0x1800000
	s_barrier

; #define PG8_STAGE(bufoff, gbase, voff) do { _Pragma("unroll") for (int _i = 0; _i < 2; ++_i) \
;         __builtin_amdgcn_global_load_lds((const unsigned*)((const char*)(gbase) + (voff)[_i]), (PG8_LAS unsigned*)(lds + (bufoff) + ldsw + _i * 8192), 16, 0, 0); } while (0)
; #define PG8_BAR __builtin_amdgcn_s_barrier()
; template <class Epi, class Sched, bool STAMP = false>
; __device__ __forceinline__ void gemm_phase(PG8_LAS unsigned char* lds, const Gemm g, const Sched& S, const Epi& E, unsigned long long* stamps) {
;     int tid_ = threadIdx.x; asm volatile("" : "+v"(tid_)); const int tid = tid_, wid = __builtin_amdgcn_readfirstlane(tid >> 6), lane = tid & 63, wr = wid >> 2, wc = wid & 3, fr = lane & 15, fq = lane >> 4;
;     const int K = g.K, nt = K / BK, LD = g.ld;
;     unsigned voffA[2], voffB[2];
; #pragma unroll
;     for (int i = 0; i < 2; ++i) { int R, C; stage_rc(tid * 16 + i * 8192, R, C); const int Rb = Epi::PERM ? ((R & ~31) + perm32(R & 31)) : R;
;         voffA[i] = (unsigned)(R * LD + C) * 2u; voffB[i] = (unsigned)(Rb * LD + C) * 2u; }
;     const size_t kstep = (size_t)(BK * 2);
;     const size_t hstep = (size_t)HALF * LD * 2;
;     const size_t tstep = 2 * hstep;
;     const unsigned ldsw = (unsigned)wid * 1024u;
;     const int aoff = lds_byte(wr * 64 + fr, fq * 8), boff = lds_byte(wc * 32 + fr, fq * 8);
;     ...
;     Unit cur, nxt; int ui = 0;
;     if (!S.next(0, cur)) return;
;     f32x4 acc[2][2][4][2];
; #pragma unroll
;     for (int a = 0; a < 2; ++a)
; #pragma unroll
;         for (int b = 0; b < 2; ++b)
; #pragma unroll
;             for (int m = 0; m < 4; ++m)
; #pragma unroll
;                 for (int n = 0; n < 2; ++n) acc[a][b][m][n] = (f32x4){0.f, 0.f, 0.f, 0.f};
;     bf16x8 At[4][2], B0[2][2], B1[2][2];
;     const char* cA = (const char*)g.A + (size_t)cur.pm * tstep; const char* cB = (const char*)g.Bt + (size_t)cur.pn * tstep;
;     S.a_ready(cur);
;     PG8_STAGE(PG8_SB(0, 0), cB, voffB); PG8_STAGE(PG8_SA(0, 0), cA, voffA); PG8_STAGE(PG8_SB(0, 1), cB + hstep, voffB); PG8_STAGE(PG8_SA(0, 1), cA + hstep, voffA);
;     if (wr == 1) PG8_BAR;
; __global__ void __launch_bounds__(512, 2) mega_fwd(Params prm) {
;     ...
;             { EpiGate<1> E; E.M = TA; E.Tm = TB; E.rowss = rs_mix; run_gemm(lds, XB, (const bf16_t*)(ws + OFF_WGB), 1024, 1024, E, T_P); }
.LBB0_343:
	v_bfe_i32 v1, v6, 27, 1
	v_lshlrev_b32_e32 v3, 4, v6
	v_lshrrev_b32_e32 v1, 22, v1
	v_ashrrev_i32_e32 v0, 31, v6
	v_add_u32_e32 v1, v3, v1
	v_lshrrev_b32_e32 v0, 26, v0
	v_and_b32_e32 v1, 0xfffffc00, v1
	v_add_u32_e32 v0, v6, v0
	v_sub_u32_e32 v1, v3, v1
	v_ashrrev_i32_e32 v0, 6, v0
	v_lshrrev_b32_e32 v2, 4, v1
	v_bitop3_b32 v2, v2, v1, 32 bitop3:0x6c
	v_lshlrev_b32_e32 v1, 3, v0
	v_and_b32_e32 v4, -16, v1
	v_ashrrev_i32_e32 v1, 31, v2
	v_lshrrev_b32_e32 v1, 26, v1
	s_waitcnt lgkmcnt(0)
	v_add_u32_e32 v5, v2, v1
	v_ashrrev_i32_e32 v1, 6, v5
	v_and_b32_e32 v5, 0xc0, v5
	v_sub_u32_e32 v2, v2, v5
	v_lshlrev_b32_e32 v7, 5, v0
	v_ashrrev_i16_sdwa v2, v188, sext(v2) dst_sel:DWORD dst_unused:UNUSED_PAD src0_sel:DWORD src1_sel:BYTE_0
	v_and_b32_e32 v7, 32, v7
	v_bfe_i32 v2, v2, 0, 16
	v_add_u32_e32 v4, v1, v4
	v_and_b32_e32 v9, 3, v1
	s_mov_b32 s3, 0x1fffe0
	v_add_lshl_u32 v7, v7, v2, 1
	v_lshlrev_b32_e32 v5, 1, v4
	v_lshrrev_b32_e32 v8, 2, v4
	v_and_or_b32 v9, v4, s3, v9
	v_lshl_add_u32 v148, v4, 11, v7
	v_add_u32_e32 v4, 0x2000, v3
	v_ashrrev_i32_e32 v3, 31, v4
	v_lshrrev_b32_e32 v3, 22, v3
	v_and_b32_e32 v5, 24, v5
	v_and_b32_e32 v8, 4, v8
	v_add_u32_e32 v3, v4, v3
	v_or3_b32 v5, v9, v8, v5
	v_ashrrev_i32_e32 v3, 10, v3
	v_lshl_add_u32 v128, v5, 11, v7
	v_mul_i32_i24_e32 v5, 0x400, v3
	v_sub_u32_e32 v4, v4, v5
	v_lshrrev_b32_e32 v5, 4, v4
	v_bitop3_b32 v5, v5, v4, 32 bitop3:0x6c
	v_lshlrev_b32_e32 v4, 3, v3
	v_and_b32_e32 v7, -16, v4
	v_ashrrev_i32_e32 v4, 31, v5
	v_lshrrev_b32_e32 v4, 26, v4
	v_add_u32_e32 v8, v5, v4
	v_ashrrev_i32_e32 v4, 6, v8
	v_add_u32_e32 v7, v4, v7
	v_and_b32_e32 v11, 3, v4
	s_add_i32 s2, s4, s2
	v_and_or_b32 v11, v7, s3, v11
	s_ashr_i32 s3, s2, 31
	s_lshr_b32 s3, s3, 27
	s_add_i32 s3, s2, s3
	s_ashr_i32 s4, s3, 5
	s_and_b32 s3, s3, 0xffe0
	s_sub_i32 s2, s2, s3
	s_bfe_i32 s3, s2, 0x80000
	s_bfe_u32 s3, s3, 0x3000c
	s_add_i32 s3, s2, s3
	s_ashr_i32 s5, s13, 8
	s_mov_b32 s70, s13
	s_ashr_i32 s12, s13, 6
	s_lshl_b32 s13, s4, 3
	s_bfe_i32 s4, s3, 0x80000
	s_and_b32 s3, s3, 0xf8
	s_sub_i32 s2, s2, s3
	s_sext_i32_i16 s4, s4
	s_sext_i32_i8 s2, s2
	s_lshr_b32 s4, s4, 3
	s_add_i32 s2, s13, s2
	s_ashr_i32 s3, s2, 31
	s_bfe_i64 s[16:17], s[4:5], 0x100000
	v_and_b32_e32 v8, 0xc0, v8
	s_lshl_b32 s88, s12, 10
	s_lshl_b64 s[14:15], s[2:3], 19
	s_lshl_b64 s[16:17], s[16:17], 19
	v_sub_u32_e32 v5, v5, v8
	s_add_u32 s58, s24, s16
	v_lshlrev_b32_e32 v9, 5, v3
	v_ashrrev_i16_sdwa v5, v188, sext(v5) dst_sel:DWORD dst_unused:UNUSED_PAD src0_sel:DWORD src1_sel:BYTE_0
	v_lshlrev_b32_e32 v8, 1, v7
	v_lshrrev_b32_e32 v10, 2, v7
	s_addc_u32 s59, s25, s17
	s_add_i32 s89, s88, 0
	v_and_b32_e32 v9, 32, v9
	v_bfe_i32 v5, v5, 0, 16
	v_and_b32_e32 v8, 24, v8
	v_and_b32_e32 v10, 4, v10
	s_add_i32 m0, s89, 0x10000
	v_or3_b32 v8, v11, v10, v8
	v_add_lshl_u32 v9, v9, v5, 1
	global_load_lds_dwordx4 v128, s[58:59]
	s_add_i32 m0, s89, 0x12000
	v_lshl_add_u32 v152, v8, 11, v9
	s_add_u32 s56, s42, s14
	global_load_lds_dwordx4 v152, s[58:59]
	s_addc_u32 s57, s43, s15
	s_mov_b32 m0, s89
	s_add_i32 s96, s89, 0x2000
	v_lshl_add_u32 v150, v7, 11, v9
	global_load_lds_dwordx4 v148, s[56:57]
	s_mov_b32 m0, s96
	s_add_u32 s14, s58, 0x40000
	global_load_lds_dwordx4 v150, s[56:57]
	s_addc_u32 s15, s59, 0
	s_add_i32 m0, s89, 0x14000
	s_nop 0
	global_load_lds_dwordx4 v128, s[14:15]
	s_add_i32 m0, s89, 0x16000
	s_nop 0
	global_load_lds_dwordx4 v152, s[14:15]
	s_add_u32 s14, s56, 0x40000
	s_addc_u32 s15, s57, 0
	s_add_i32 s97, s89, 0x4000
	s_mov_b32 m0, s97
	s_add_i32 s64, s89, 0x6000
	global_load_lds_dwordx4 v148, s[14:15]
	s_mov_b32 m0, s64
	s_cmp_lg_u32 s5, 1
	global_load_lds_dwordx4 v150, s[14:15]
	s_cbranch_scc1 .LBB0_345
	s_barrier
	s_setprio 1

; #define PG8_WAIT_V(n) asm volatile("s_waitcnt vmcnt(" #n ")" ::: "memory")
; #define PG8_BAR __builtin_amdgcn_s_barrier()
; template <class Epi, class Sched, bool STAMP = false>
; __device__ __forceinline__ void gemm_phase(PG8_LAS unsigned char* lds, const Gemm g, const Sched& S, const Epi& E, unsigned long long* stamps) {
;     ...
;     PG8_WAIT_V(0);
;     if (wr == 0) PG8_BAR;
;     PG8_BAR;
.LBB0_357:
	s_setprio 0
	v_readlane_b32 s46, v242, 24
	v_readlane_b32 s88, v242, 39
	v_readlane_b32 s47, v242, 25
	s_movk_i32 s77, 0xa0
	s_movk_i32 s58, 0xff60
	s_mov_b32 s62, 0x1800000
	v_readlane_b32 s89, v242, 40
	s_mov_b32 s70, s75
	s_barrier

; #define PG8_BAR __builtin_amdgcn_s_barrier()
; template <class Epi, class Sched, bool STAMP = false>
; __device__ __forceinline__ void gemm_phase(PG8_LAS unsigned char* lds, const Gemm g, const Sched& S, const Epi& E, unsigned long long* stamps) {
;     int tid_ = threadIdx.x; asm volatile("" : "+v"(tid_)); const int tid = tid_, wid = __builtin_amdgcn_readfirstlane(tid >> 6), lane = tid & 63, wr = wid >> 2, wc = wid & 3, fr = lane & 15, fq = lane >> 4;
;     const int K = g.K, nt = K / BK, LD = g.ld;
;     unsigned voffA[2], voffB[2];
; #pragma unroll
;     for (int i = 0; i < 2; ++i) { int R, C; stage_rc(tid * 16 + i * 8192, R, C); const int Rb = Epi::PERM ? ((R & ~31) + perm32(R & 31)) : R;
;         voffA[i] = (unsigned)(R * LD + C) * 2u; voffB[i] = (unsigned)(Rb * LD + C) * 2u; }
;     const size_t kstep = (size_t)(BK * 2);
;     const size_t hstep = (size_t)HALF * LD * 2;
;     const size_t tstep = 2 * hstep;
;     const unsigned ldsw = (unsigned)wid * 1024u;
;     const int aoff = lds_byte(wr * 64 + fr, fq * 8), boff = lds_byte(wc * 32 + fr, fq * 8);
;     ...
;     Unit cur, nxt; int ui = 0;
;     if (!S.next(0, cur)) return;
;     f32x4 acc[2][2][4][2];
; #pragma unroll
;     for (int a = 0; a < 2; ++a)
; #pragma unroll
;         for (int b = 0; b < 2; ++b)
; #pragma unroll
;             for (int m = 0; m < 4; ++m)
; #pragma unroll
;                 for (int n = 0; n < 2; ++n) acc[a][b][m][n] = (f32x4){0.f, 0.f, 0.f, 0.f};
;     bf16x8 At[4][2], B0[2][2], B1[2][2];
;     const char* cA = (const char*)g.A + (size_t)cur.pm * tstep; const char* cB = (const char*)g.Bt + (size_t)cur.pn * tstep;
;     S.a_ready(cur);
;     PG8_STAGE(PG8_SB(0, 0), cB, voffB); PG8_STAGE(PG8_SA(0, 0), cA, voffA); PG8_STAGE(PG8_SB(0, 1), cB + hstep, voffB); PG8_STAGE(PG8_SA(0, 1), cA + hstep, voffA);
;     if (wr == 1) PG8_BAR;
; __device__ __forceinline__ void run_gate_sample_tasks(LAS unsigned char* lds, unsigned char* ws) {
;     const int t = bidx(); OneUnit S; S.valid = t < 192;
;     const bf16_t* A; const bf16_t* Bt; int ld, slot, u, sl;
;     if (t < 32)       { u = t >> 1; sl = t & 1; A = (const bf16_t*)(ws + OFF_B); Bt = (const bf16_t*)(ws + OFF_WOA); ld = 512; slot = sl; }
;     else if (t < 64)  { u = (t - 32) >> 1; sl = t & 1; A = (const bf16_t*)(ws + OFF_B + SLOT); Bt = (const bf16_t*)(ws + OFF_WOB); ld = 512; slot = 2 + sl; }
.LBB0_370:
	s_add_u32 s2, s91, 0xbb00000
	s_addc_u32 s3, s79, 0
	v_mov_b32_e32 v0, v184
	s_cmpk_gt_i32 s4, 0xbf
	s_nop 0
	v_readfirstlane_b32 s38, v0
	s_cbranch_scc1 .LBB0_378
	v_lshlrev_b32_e32 v1, 4, v0
	v_add_u32_e32 v2, 0x2000, v1
	v_ashrrev_i32_e32 v3, 31, v2
	v_lshrrev_b32_e32 v3, 22, v3
	v_add_u32_e32 v3, v2, v3
	v_ashrrev_i32_e32 v3, 10, v3
	v_mul_i32_i24_e32 v4, 0x400, v3
	v_sub_u32_e32 v2, v2, v4
	v_lshrrev_b32_e32 v4, 4, v2
	v_bitop3_b32 v2, v4, v2, 32 bitop3:0x6c
	v_ashrrev_i32_e32 v4, 31, v2
	v_lshrrev_b32_e32 v4, 26, v4
	v_add_u32_e32 v4, v2, v4
	v_lshlrev_b32_e32 v6, 3, v3
	s_waitcnt lgkmcnt(0)
	v_ashrrev_i32_e32 v5, 6, v4
	v_and_b32_e32 v6, 0x7ffffff0, v6
	v_and_b32_e32 v4, 0xc0, v4
	v_add_u32_e32 v5, v5, v6
	v_sub_u32_e32 v2, v2, v4
	v_mul_lo_u32 v5, v5, s13
	v_lshlrev_b32_e32 v3, 5, v3
	v_ashrrev_i16_sdwa v2, v188, sext(v2) dst_sel:DWORD dst_unused:UNUSED_PAD src0_sel:DWORD src1_sel:BYTE_0
	v_and_or_b32 v3, v3, 32, v5
	v_bfe_i32 v2, v2, 0, 16
	v_add_lshl_u32 v148, v3, v2, 1
	v_bfe_i32 v2, v0, 27, 1
	v_lshrrev_b32_e32 v2, 22, v2
	v_add_u32_e32 v2, v1, v2
	v_and_b32_e32 v2, 0xfffffc00, v2
	v_sub_u32_e32 v1, v1, v2
	v_lshrrev_b32_e32 v2, 4, v1
	v_ashrrev_i32_e32 v4, 31, v0
	v_bitop3_b32 v1, v2, v1, 32 bitop3:0x6c
	v_lshrrev_b32_e32 v4, 26, v4
	s_ashr_i32 s44, s12, 2
	s_ashr_i32 s14, s38, 6
	v_ashrrev_i32_e32 v2, 31, v1
	v_add_u32_e32 v4, v0, v4
	s_add_i32 s44, s44, 64
	s_and_b32 s39, s12, 3
	s_ashr_i32 s15, s38, 8
	s_lshl_b32 s45, s13, 8
	s_lshl_b32 s46, s14, 10
	s_lshl_b32 s4, s5, 9
	v_lshrrev_b32_e32 v2, 26, v2
	v_ashrrev_i32_e32 v4, 6, v4
	s_add_u32 s5, s24, s4
	v_add_u32_e32 v2, v1, v2
	v_lshlrev_b32_e32 v5, 3, v4
	s_addc_u32 s6, s25, 0
	v_ashrrev_i32_e32 v3, 6, v2
	v_and_b32_e32 v5, 0x7ffffff0, v5
	s_add_u32 s7, s42, s4
	v_add_u32_e32 v3, v3, v5
	s_addc_u32 s12, s43, 0
	s_lshl_b32 s4, s13, 9
	v_mul_lo_u32 v3, v3, s13
	s_ashr_i32 s13, s44, 31
	v_and_b32_e32 v2, 0xc0, v2
	s_mul_hi_u32 s16, s4, s44
	s_mul_i32 s13, s4, s13
	v_sub_u32_e32 v1, v1, v2
	s_add_i32 s16, s16, s13
	s_mul_i32 s13, s4, s44
	s_mul_i32 s4, s4, s39
	v_lshlrev_b32_e32 v4, 5, v4
	v_ashrrev_i16_sdwa v1, v188, sext(v1) dst_sel:DWORD dst_unused:UNUSED_PAD src0_sel:DWORD src1_sel:BYTE_0
	s_add_u32 s4, s5, s4
	v_and_or_b32 v3, v4, 32, v3
	v_bfe_i32 v1, v1, 0, 16
	s_addc_u32 s5, s6, 0
	s_add_i32 s42, s46, 0
	v_add_lshl_u32 v128, v3, v1, 1
	s_add_i32 m0, s42, 0x10000
	s_nop 0
	global_load_lds_dwordx4 v128, s[4:5]
	s_add_i32 m0, s42, 0x12000
	s_add_u32 s6, s7, s13
	global_load_lds_dwordx4 v148, s[4:5]
	s_addc_u32 s7, s12, s16
	s_mov_b32 m0, s42
	s_add_i32 s43, s42, 0x2000
	global_load_lds_dwordx4 v128, s[6:7]
	s_mov_b32 m0, s43
	s_add_u32 s20, s4, s45
	global_load_lds_dwordx4 v148, s[6:7]
	s_addc_u32 s21, s5, 0
	s_add_i32 m0, s42, 0x14000
	s_nop 0
	global_load_lds_dwordx4 v128, s[20:21]
	s_add_i32 m0, s42, 0x16000
	s_add_u32 s12, s6, s45
	s_addc_u32 s13, s7, 0
	s_add_i32 s47, s42, 0x4000
	global_load_lds_dwordx4 v148, s[20:21]
	s_mov_b32 m0, s47
	s_add_i32 s48, s42, 0x6000
	global_load_lds_dwordx4 v128, s[12:13]
	s_mov_b32 m0, s48
	s_cmp_lg_u32 s15, 1
	global_load_lds_dwordx4 v148, s[12:13]
	s_cbranch_scc1 .LBB0_373
	s_barrier
	s_setprio 1

; #define PG8_WAIT_V(n) asm volatile("s_waitcnt vmcnt(" #n ")" ::: "memory")
; #define PG8_BAR __builtin_amdgcn_s_barrier()
; template <class Epi, class Sched, bool STAMP = false>
; __device__ __forceinline__ void gemm_phase(PG8_LAS unsigned char* lds, const Gemm g, const Sched& S, const Epi& E, unsigned long long* stamps) {
;     ...
;     PG8_WAIT_V(0);
;     if (wr == 0) PG8_BAR;
;     PG8_BAR;
.LBB0_377:
	s_setprio 0
	v_readlane_b32 s46, v242, 24
	v_readlane_b32 s47, v242, 25
	v_readlane_b32 s52, v242, 26
	v_readlane_b32 s29, v242, 27
	s_movk_i32 s58, 0xff60
	s_mov_b32 s62, 0x1800000
	s_barrier

; #define PG8_STAGE(bufoff, gbase, voff) do { _Pragma("unroll") for (int _i = 0; _i < 2; ++_i) \
;         __builtin_amdgcn_global_load_lds((const unsigned*)((const char*)(gbase) + (voff)[_i]), (PG8_LAS unsigned*)(lds + (bufoff) + ldsw + _i * 8192), 16, 0, 0); } while (0)
; #define PG8_BAR __builtin_amdgcn_s_barrier()
; template <class Epi, class Sched, bool STAMP = false>
; __device__ __forceinline__ void gemm_phase(PG8_LAS unsigned char* lds, const Gemm g, const Sched& S, const Epi& E, unsigned long long* stamps) {
;     int tid_ = threadIdx.x; asm volatile("" : "+v"(tid_)); const int tid = tid_, wid = __builtin_amdgcn_readfirstlane(tid >> 6), lane = tid & 63, wr = wid >> 2, wc = wid & 3, fr = lane & 15, fq = lane >> 4;
;     const int K = g.K, nt = K / BK, LD = g.ld;
;     unsigned voffA[2], voffB[2];
; #pragma unroll
;     for (int i = 0; i < 2; ++i) { int R, C; stage_rc(tid * 16 + i * 8192, R, C); const int Rb = Epi::PERM ? ((R & ~31) + perm32(R & 31)) : R;
;         voffA[i] = (unsigned)(R * LD + C) * 2u; voffB[i] = (unsigned)(Rb * LD + C) * 2u; }
;     const size_t kstep = (size_t)(BK * 2);
;     const size_t hstep = (size_t)HALF * LD * 2;
;     const size_t tstep = 2 * hstep;
;     const unsigned ldsw = (unsigned)wid * 1024u;
;     const int aoff = lds_byte(wr * 64 + fr, fq * 8), boff = lds_byte(wc * 32 + fr, fq * 8);
;     ...
;     Unit cur, nxt; int ui = 0;
;     if (!S.next(0, cur)) return;
;     f32x4 acc[2][2][4][2];
; #pragma unroll
;     for (int a = 0; a < 2; ++a)
; #pragma unroll
;         for (int b = 0; b < 2; ++b)
; #pragma unroll
;             for (int m = 0; m < 4; ++m)
; #pragma unroll
;                 for (int n = 0; n < 2; ++n) acc[a][b][m][n] = (f32x4){0.f, 0.f, 0.f, 0.f};
;     bf16x8 At[4][2], B0[2][2], B1[2][2];
;     const char* cA = (const char*)g.A + (size_t)cur.pm * tstep; const char* cB = (const char*)g.Bt + (size_t)cur.pn * tstep;
;     S.a_ready(cur);
;     PG8_STAGE(PG8_SB(0, 0), cB, voffB); PG8_STAGE(PG8_SA(0, 0), cA, voffA); PG8_STAGE(PG8_SB(0, 1), cB + hstep, voffB); PG8_STAGE(PG8_SA(0, 1), cA + hstep, voffA);
;     if (wr == 1) PG8_BAR;
; __global__ void __launch_bounds__(512, 2) mega_fwd(Params prm) {
;     ...
;         case 6: { GEMM_PRO; EpiBf<0> E; E.O = (bf16_t*)(ws + OFF_A); E.ldc = 2048; E.rowss = rs_mix; run_gemm(lds, XB, (const bf16_t*)(ws + OFF_WHG), 2048, 1024, E);
.LBB0_487:
	s_andn2_b64 vcc, exec, s[0:1]
	s_cbranch_vccnz .LBB0_547
	s_mov_b32 s2, s86
	s_mov_b32 s3, s87
	s_mov_b32 s10, s90
	v_mov_b32_e32 v14, v184
	s_cmpk_gt_i32 s10, 0x21f
	v_readfirstlane_b32 s36, v14
	s_cbranch_scc1 .LBB0_500
	v_lshlrev_b32_e32 v0, 4, v14
	v_add_u32_e32 v1, 0x2000, v0
	v_ashrrev_i32_e32 v2, 31, v1
	v_lshrrev_b32_e32 v2, 22, v2
	v_add_u32_e32 v2, v1, v2
	v_ashrrev_i32_e32 v8, 10, v2
	v_mul_i32_i24_e32 v2, 0x400, v8
	v_sub_u32_e32 v1, v1, v2
	v_lshrrev_b32_e32 v2, 4, v1
	v_bitop3_b32 v1, v2, v1, 32 bitop3:0x6c
	v_ashrrev_i32_e32 v2, 31, v1
	v_lshrrev_b32_e32 v2, 26, v2
	v_add_u32_e32 v2, v1, v2
	v_lshlrev_b32_e32 v3, 3, v8
	v_ashrrev_i32_e32 v9, 6, v2
	v_and_b32_e32 v3, -16, v3
	v_add_u32_e32 v3, v9, v3
	v_and_b32_e32 v4, 3, v9
	s_mov_b32 s0, 0x1fffe0
	s_waitcnt lgkmcnt(0)
	v_lshrrev_b32_e32 v5, 2, v3
	v_lshlrev_b32_e32 v6, 1, v3
	v_and_b32_e32 v2, 0xc0, v2
	v_and_or_b32 v4, v3, s0, v4
	v_and_b32_e32 v5, 4, v5
	v_and_b32_e32 v6, 24, v6
	v_sub_u32_e32 v1, v1, v2
	v_or3_b32 v4, v4, v5, v6
	v_lshlrev_b32_e32 v5, 5, v8
	v_ashrrev_i16_sdwa v1, v188, sext(v1) dst_sel:DWORD dst_unused:UNUSED_PAD src0_sel:DWORD src1_sel:BYTE_0
	v_and_b32_e32 v5, 32, v5
	v_bfe_i32 v10, v1, 0, 16
	v_add_lshl_u32 v1, v5, v10, 1
	v_lshl_add_u32 v148, v4, 11, v1
	v_lshl_add_u32 v150, v3, 11, v1
	v_bfe_i32 v1, v14, 27, 1
	v_lshrrev_b32_e32 v1, 22, v1
	v_add_u32_e32 v1, v0, v1
	v_and_b32_e32 v1, 0xfffffc00, v1
	v_sub_u32_e32 v0, v0, v1
	v_lshrrev_b32_e32 v1, 4, v0
	v_ashrrev_i32_e32 v2, 31, v14
	v_bitop3_b32 v0, v1, v0, 32 bitop3:0x6c
	v_lshrrev_b32_e32 v2, 26, v2
	v_ashrrev_i32_e32 v1, 31, v0
	v_add_u32_e32 v2, v14, v2
	s_add_u32 s37, s2, 0x2200000
	v_lshrrev_b32_e32 v1, 26, v1
	v_ashrrev_i32_e32 v12, 6, v2
	s_addc_u32 s40, s3, 0
	v_add_u32_e32 v1, v0, v1
	v_lshlrev_b32_e32 v2, 3, v12
	s_add_u32 s41, s2, 0x400000
	v_ashrrev_i32_e32 v11, 6, v1
	v_and_b32_e32 v2, -16, v2
	s_addc_u32 s42, s3, 0
	v_add_u32_e32 v2, v11, v2
	v_and_b32_e32 v3, 3, v11
	s_ashr_i32 s44, s10, 31
	v_and_or_b32 v3, v2, s0, v3
	s_lshr_b32 s0, s44, 29
	s_add_i32 s0, s10, s0
	s_ashr_i32 s4, s36, 6
	s_ashr_i32 s1, s0, 3
	s_and_b32 s0, s0, -8
	s_ashr_i32 s5, s36, 8
	s_lshl_b32 s43, s4, 10
	s_sub_i32 s0, s10, s0
	s_cmp_lt_i32 s0, 0
	s_movk_i32 s6, 0x45
	s_cselect_b32 s6, s6, 0x44
	s_mul_i32 s0, s6, s0
	s_add_i32 s0, s0, s1
	s_ashr_i32 s1, s0, 31
	s_lshr_b32 s1, s1, 26
	v_lshrrev_b32_e32 v4, 2, v2
	v_lshlrev_b32_e32 v5, 1, v2
	v_and_b32_e32 v1, 0xc0, v1
	s_add_i32 s1, s0, s1
	v_and_b32_e32 v4, 4, v4
	v_and_b32_e32 v5, 24, v5
	v_sub_u32_e32 v0, v0, v1
	s_ashr_i32 s6, s1, 6
	v_or3_b32 v3, v3, v4, v5
	v_lshlrev_b32_e32 v4, 5, v12
	v_ashrrev_i16_sdwa v0, v188, sext(v0) dst_sel:DWORD dst_unused:UNUSED_PAD src0_sel:DWORD src1_sel:BYTE_0
	s_lshl_b32 s6, s6, 3
	v_and_b32_e32 v4, 32, v4
	v_bfe_i32 v13, v0, 0, 16
	s_sub_i32 s7, 0x44, s6
	v_add_lshl_u32 v0, v4, v13, 1
	s_min_u32 s7, s7, 8
	s_andn2_b32 s1, s1, 63
	v_lshl_add_u32 v128, v3, 11, v0
	s_sub_i32 s12, s0, s1
	v_cvt_f32_ubyte0_e32 v3, s7
	v_cvt_f32_i32_e32 v1, s12
	v_rcp_iflag_f32_e32 v4, v3
	v_lshl_add_u32 v152, v2, 11, v0
	s_ashr_i32 s0, s12, 30
	s_or_b32 s13, s0, 1
	v_mul_f32_e32 v0, v1, v4
	v_trunc_f32_e32 v0, v0
	v_fma_f32 v1, -v0, v3, v1
	v_cvt_i32_f32_e32 v0, v0
	v_cmp_ge_f32_e64 s[0:1], |v1|, v3
	s_and_b64 s[0:1], s[0:1], exec
	s_cselect_b32 s0, s13, 0
	v_readfirstlane_b32 s1, v0
	s_add_i32 s0, s1, s0
	s_mul_i32 s1, s0, s7
	s_sub_i32 s1, s12, s1
	s_sext_i32_i8 s1, s1
	s_add_i32 s22, s6, s1
	s_ashr_i32 s23, s22, 31
	s_bfe_i64 s[12:13], s[0:1], 0x80000
	s_lshl_b64 s[6:7], s[22:23], 19
	s_lshl_b64 s[12:13], s[12:13], 19
	s_add_u32 s26, s41, s12
	s_addc_u32 s27, s42, s13
	s_add_i32 s23, s43, 0
	s_add_i32 m0, s23, 0x10000
	v_mov_b32_e32 v149, v129
	global_load_lds_dwordx4 v128, s[26:27]
	s_add_i32 m0, s23, 0x12000
	s_add_u32 s24, s37, s6
	global_load_lds_dwordx4 v148, s[26:27]
	s_addc_u32 s25, s40, s7
	s_mov_b32 m0, s23
	s_add_i32 s45, s23, 0x2000
	global_load_lds_dwordx4 v152, s[24:25]
	s_mov_b32 m0, s45
	s_add_u32 s6, s26, 0x40000
	global_load_lds_dwordx4 v150, s[24:25]
	s_addc_u32 s7, s27, 0
	s_add_i32 m0, s23, 0x14000
	v_mov_b32_e32 v153, v129
	global_load_lds_dwordx4 v128, s[6:7]
	s_add_i32 m0, s23, 0x16000
	v_mov_b32_e32 v151, v129
	global_load_lds_dwordx4 v148, s[6:7]
	s_add_u32 s6, s24, 0x40000
	s_addc_u32 s7, s25, 0
	s_add_i32 s46, s23, 0x4000
	s_mov_b32 m0, s46
	s_add_i32 s47, s23, 0x6000
	global_load_lds_dwordx4 v152, s[6:7]
	s_mov_b32 m0, s47
	s_mov_b32 s63, s65
	global_load_lds_dwordx4 v150, s[6:7]
	v_lshl_add_u64 v[6:7], s[26:27], 0, v[128:129]
	v_lshl_add_u64 v[4:5], s[26:27], 0, v[148:149]
	v_lshl_add_u64 v[2:3], s[24:25], 0, v[152:153]
	s_cmp_lg_u32 s5, 1
	v_lshl_add_u64 v[0:1], s[24:25], 0, v[150:151]
	s_cbranch_scc1 .LBB0_491
	s_barrier
	s_setprio 1

; #define PG8_WAIT_V(n) asm volatile("s_waitcnt vmcnt(" #n ")" ::: "memory")
; #define PG8_BAR __builtin_amdgcn_s_barrier()
; template <class Epi, class Sched, bool STAMP = false>
; __device__ __forceinline__ void gemm_phase(PG8_LAS unsigned char* lds, const Gemm g, const Sched& S, const Epi& E, unsigned long long* stamps) {
;     ...
;     PG8_WAIT_V(0);
;     if (wr == 0) PG8_BAR;
;     PG8_BAR;
.LBB0_499:
	s_setprio 0
	v_readlane_b32 s46, v242, 24
	v_readlane_b32 s47, v242, 25
	s_movk_i32 s58, 0xff60
	s_mov_b32 s65, s63
	s_barrier

; #define PG8_BAR __builtin_amdgcn_s_barrier()
; __device__ __forceinline__ int bidx() { int b = blockIdx.x; asm volatile("" : "+s"(b)); return b; }
; template <class Epi, class Sched, bool STAMP = false>
; __device__ __forceinline__ void gemm_phase(PG8_LAS unsigned char* lds, const Gemm g, const Sched& S, const Epi& E, unsigned long long* stamps) {
;     int tid_ = threadIdx.x; asm volatile("" : "+v"(tid_)); const int tid = tid_, wid = __builtin_amdgcn_readfirstlane(tid >> 6), lane = tid & 63, wr = wid >> 2, wc = wid & 3, fr = lane & 15, fq = lane >> 4;
;     const int K = g.K, nt = K / BK, LD = g.ld;
;     unsigned voffA[2], voffB[2];
; #pragma unroll
;     for (int i = 0; i < 2; ++i) { int R, C; stage_rc(tid * 16 + i * 8192, R, C); const int Rb = Epi::PERM ? ((R & ~31) + perm32(R & 31)) : R;
;         voffA[i] = (unsigned)(R * LD + C) * 2u; voffB[i] = (unsigned)(Rb * LD + C) * 2u; }
;     const size_t kstep = (size_t)(BK * 2);
;     const size_t hstep = (size_t)HALF * LD * 2;
;     const size_t tstep = 2 * hstep;
;     const unsigned ldsw = (unsigned)wid * 1024u;
;     const int aoff = lds_byte(wr * 64 + fr, fq * 8), boff = lds_byte(wc * 32 + fr, fq * 8);
;     ...
;     Unit cur, nxt; int ui = 0;
;     if (!S.next(0, cur)) return;
;     f32x4 acc[2][2][4][2];
; #pragma unroll
;     for (int a = 0; a < 2; ++a)
; #pragma unroll
;         for (int b = 0; b < 2; ++b)
; #pragma unroll
;             for (int m = 0; m < 4; ++m)
; #pragma unroll
;                 for (int n = 0; n < 2; ++n) acc[a][b][m][n] = (f32x4){0.f, 0.f, 0.f, 0.f};
;     bf16x8 At[4][2], B0[2][2], B1[2][2];
;     const char* cA = (const char*)g.A + (size_t)cur.pm * tstep; const char* cB = (const char*)g.Bt + (size_t)cur.pn * tstep;
;     S.a_ready(cur);
;     PG8_STAGE(PG8_SB(0, 0), cB, voffB); PG8_STAGE(PG8_SA(0, 0), cA, voffA); PG8_STAGE(PG8_SB(0, 1), cB + hstep, voffB); PG8_STAGE(PG8_SA(0, 1), cA + hstep, voffA);
;     if (wr == 1) PG8_BAR;
; __device__ __forceinline__ void run_ffn_down(LAS unsigned char* lds, const bf16_t* HID, const bf16_t* WDN, const EpiResid& E, float* PART) {
;     { pg8::StaticOrder S; S.init(T_P, 1024, (int)gridDim.x, bidx());
;       pg8::Gemm g; g.A = HID; g.Bt = WDN; g.M = T_P; g.N = 1024; g.K = 4096; g.ld = 4096;
;       pg8::gemm_phase<EpiResid, pg8::StaticOrder, false>(lds, g, S, E, nullptr); }
.LBB0_1171:
	s_add_u32 s45, s10, 0x5500000
	s_addc_u32 s46, s42, 0
	s_add_u32 s47, s10, 0x1800000
	s_addc_u32 s48, s42, 0
	s_andn2_b64 vcc, exec, s[0:1]
	s_cbranch_vccnz .LBB0_1203
	v_ashrrev_i32_e32 v1, 31, v9
	v_lshrrev_b32_e32 v1, 26, v1
	v_add_u32_e32 v1, v9, v1
	v_ashrrev_i32_e32 v8, 6, v1
	v_bfe_i32 v1, v9, 27, 1
	v_lshlrev_b32_e32 v0, 4, v9
	v_lshrrev_b32_e32 v1, 22, v1
	v_add_u32_e32 v1, v0, v1
	v_and_b32_e32 v1, 0xfffffc00, v1
	v_sub_u32_e32 v1, v0, v1
	v_lshrrev_b32_e32 v2, 4, v1
	v_bitop3_b32 v1, v2, v1, 32 bitop3:0x6c
	v_ashrrev_i32_e32 v3, 31, v1
	v_lshrrev_b32_e32 v3, 26, v3
	v_add_u32_e32 v3, v1, v3
	v_lshlrev_b32_e32 v2, 3, v8
	v_ashrrev_i32_e32 v10, 6, v3
	v_and_b32_e32 v3, 0xc0, v3
	v_and_b32_e32 v2, 0x7fff0, v2
	v_lshlrev_b32_e32 v4, 5, v8
	v_sub_u32_e32 v1, v1, v3
	v_add_u32_e32 v2, v10, v2
	v_and_b32_e32 v11, 32, v4
	v_ashrrev_i16_sdwa v1, v188, sext(v1) dst_sel:DWORD dst_unused:UNUSED_PAD src0_sel:DWORD src1_sel:BYTE_0
	s_waitcnt lgkmcnt(0)
	v_bfe_i32 v12, v1, 0, 16
	v_lshl_or_b32 v1, v2, 12, v11
	v_add_u32_e32 v0, 0x2000, v0
	v_add_lshl_u32 v128, v1, v12, 1
	v_ashrrev_i32_e32 v1, 31, v0
	v_lshrrev_b32_e32 v1, 22, v1
	v_add_u32_e32 v1, v0, v1
	v_ashrrev_i32_e32 v13, 10, v1
	v_mul_i32_i24_e32 v1, 0x400, v13
	v_sub_u32_e32 v0, v0, v1
	v_lshrrev_b32_e32 v1, 4, v0
	v_bitop3_b32 v0, v1, v0, 32 bitop3:0x6c
	v_ashrrev_i32_e32 v2, 31, v0
	v_lshrrev_b32_e32 v2, 26, v2
	s_ashr_i32 s5, s44, 6
	s_ashr_i32 s23, s22, 31
	s_ashr_i32 s25, s24, 31
	s_ashr_i32 s4, s44, 8
	v_add_u32_e32 v2, v0, v2
	s_lshl_b32 s49, s5, 10
	s_lshl_b64 s[0:1], s[22:23], 21
	s_lshl_b64 s[2:3], s[24:25], 21
	v_lshlrev_b32_e32 v1, 3, v13
	v_ashrrev_i32_e32 v14, 6, v2
	v_and_b32_e32 v2, 0xc0, v2
	s_add_u32 s30, s47, s2
	v_and_b32_e32 v1, 0x7fff0, v1
	v_lshlrev_b32_e32 v3, 5, v13
	v_sub_u32_e32 v0, v0, v2
	s_addc_u32 s31, s48, s3
	s_add_i32 s25, s49, 0
	v_add_u32_e32 v1, v14, v1
	v_and_b32_e32 v15, 32, v3
	v_ashrrev_i16_sdwa v0, v188, sext(v0) dst_sel:DWORD dst_unused:UNUSED_PAD src0_sel:DWORD src1_sel:BYTE_0
	s_add_i32 m0, s25, 0x10000
	v_bfe_i32 v16, v0, 0, 16
	v_lshl_or_b32 v0, v1, 12, v15
	global_load_lds_dwordx4 v128, s[30:31]
	s_add_i32 m0, s25, 0x12000
	v_add_lshl_u32 v148, v0, v16, 1
	s_add_u32 s26, s45, s0
	global_load_lds_dwordx4 v148, s[30:31]
	s_addc_u32 s27, s46, s1
	s_mov_b32 m0, s25
	s_add_i32 s53, s25, 0x2000
	global_load_lds_dwordx4 v128, s[26:27]
	s_mov_b32 m0, s53
	s_add_u32 s0, s30, 0x100000
	global_load_lds_dwordx4 v148, s[26:27]
	s_addc_u32 s1, s31, 0
	s_add_i32 m0, s25, 0x14000
	v_mov_b32_e32 v149, v129
	global_load_lds_dwordx4 v128, s[0:1]
	s_add_i32 m0, s25, 0x16000
	v_lshl_add_u64 v[6:7], s[30:31], 0, v[128:129]
	global_load_lds_dwordx4 v148, s[0:1]
	s_add_u32 s0, s26, 0x100000
	s_addc_u32 s1, s27, 0
	s_add_i32 s56, s25, 0x4000
	s_mov_b32 m0, s56
	s_add_i32 s57, s25, 0x6000
	global_load_lds_dwordx4 v128, s[0:1]
	s_mov_b32 m0, s57
	v_lshl_add_u64 v[4:5], s[30:31], 0, v[148:149]
	global_load_lds_dwordx4 v148, s[0:1]
	v_lshl_add_u64 v[2:3], s[26:27], 0, v[128:129]
	s_cmp_lg_u32 s4, 1
	v_lshl_add_u64 v[0:1], s[26:27], 0, v[148:149]
	s_cbranch_scc1 .LBB0_1174
	s_barrier
	s_setprio 1

; #define PG8_BAR __builtin_amdgcn_s_barrier()
; template <class Epi, class Sched, bool STAMP = false>
; __device__ __forceinline__ void gemm_phase(PG8_LAS unsigned char* lds, const Gemm g, const Sched& S, const Epi& E, unsigned long long* stamps) {
;     int tid_ = threadIdx.x; asm volatile("" : "+v"(tid_)); const int tid = tid_, wid = __builtin_amdgcn_readfirstlane(tid >> 6), lane = tid & 63, wr = wid >> 2, wc = wid & 3, fr = lane & 15, fq = lane >> 4;
;     const int K = g.K, nt = K / BK, LD = g.ld;
;     unsigned voffA[2], voffB[2];
; #pragma unroll
;     for (int i = 0; i < 2; ++i) { int R, C; stage_rc(tid * 16 + i * 8192, R, C); const int Rb = Epi::PERM ? ((R & ~31) + perm32(R & 31)) : R;
;         voffA[i] = (unsigned)(R * LD + C) * 2u; voffB[i] = (unsigned)(Rb * LD + C) * 2u; }
;     const size_t kstep = (size_t)(BK * 2);
;     const size_t hstep = (size_t)HALF * LD * 2;
;     const size_t tstep = 2 * hstep;
;     const unsigned ldsw = (unsigned)wid * 1024u;
;     const int aoff = lds_byte(wr * 64 + fr, fq * 8), boff = lds_byte(wc * 32 + fr, fq * 8);
;     ...
;     Unit cur, nxt; int ui = 0;
;     if (!S.next(0, cur)) return;
;     f32x4 acc[2][2][4][2];
; #pragma unroll
;     for (int a = 0; a < 2; ++a)
; #pragma unroll
;         for (int b = 0; b < 2; ++b)
; #pragma unroll
;             for (int m = 0; m < 4; ++m)
; #pragma unroll
;                 for (int n = 0; n < 2; ++n) acc[a][b][m][n] = (f32x4){0.f, 0.f, 0.f, 0.f};
;     bf16x8 At[4][2], B0[2][2], B1[2][2];
;     const char* cA = (const char*)g.A + (size_t)cur.pm * tstep; const char* cB = (const char*)g.Bt + (size_t)cur.pn * tstep;
;     S.a_ready(cur);
;     PG8_STAGE(PG8_SB(0, 0), cB, voffB); PG8_STAGE(PG8_SA(0, 0), cA, voffA); PG8_STAGE(PG8_SB(0, 1), cB + hstep, voffB); PG8_STAGE(PG8_SA(0, 1), cA + hstep, voffA);
;     if (wr == 1) PG8_BAR;
; __device__ __forceinline__ void run_ffn_down(LAS unsigned char* lds, const bf16_t* HID, const bf16_t* WDN, const EpiResid& E, float* PART) {
;     ...
;     { const int t = bidx(); OneUnit S; S.valid = t < 128; const int sl = t & 7, u = (t >> 3) & 15; S.pm = 64 + (u >> 2); S.pn = u & 3;
;       pg8::Gemm g; g.A = HID + sl * 512; g.Bt = WDN + sl * 512; g.M = T_ALL; g.N = 1024; g.K = 512; g.ld = 4096;
;       EpiPartial EA; EA.PART = PART + (size_t)sl * 1024 * 1024; EA.ldp = 1024;
;       pg8::gemm_phase<EpiPartial, OneUnit, false>(lds, g, S, EA, nullptr); }
.LBB0_1203:
	s_mov_b32 s4, s90
	s_waitcnt lgkmcnt(0)
	v_mov_b32_e32 v12, v184
	s_cmpk_gt_i32 s4, 0x7f
	s_nop 0
	v_readfirstlane_b32 s22, v12
	s_cbranch_scc1 .LBB0_1211
	v_lshlrev_b32_e32 v0, 4, v12
	v_add_u32_e32 v1, 0x2000, v0
	v_ashrrev_i32_e32 v2, 31, v1
	v_lshrrev_b32_e32 v2, 22, v2
	v_add_u32_e32 v2, v1, v2
	v_ashrrev_i32_e32 v8, 10, v2
	v_mul_i32_i24_e32 v2, 0x400, v8
	v_sub_u32_e32 v1, v1, v2
	v_lshrrev_b32_e32 v2, 4, v1
	v_bitop3_b32 v1, v2, v1, 32 bitop3:0x6c
	v_ashrrev_i32_e32 v2, 31, v1
	v_lshrrev_b32_e32 v2, 26, v2
	v_add_u32_e32 v2, v1, v2
	v_ashrrev_i32_e32 v9, 6, v2
	v_and_b32_e32 v2, 0xc0, v2
	v_sub_u32_e32 v1, v1, v2
	v_ashrrev_i16_sdwa v1, v188, sext(v1) dst_sel:DWORD dst_unused:UNUSED_PAD src0_sel:DWORD src1_sel:BYTE_0
	v_bfe_i32 v11, v1, 0, 16
	v_bfe_i32 v1, v12, 27, 1
	v_lshrrev_b32_e32 v1, 22, v1
	v_add_u32_e32 v1, v0, v1
	v_and_b32_e32 v1, 0xfffffc00, v1
	v_sub_u32_e32 v0, v0, v1
	v_lshrrev_b32_e32 v1, 4, v0
	s_and_b32 s25, s4, 7
	s_bfe_u32 s0, s4, 0x20005
	s_ashr_i32 s6, s22, 6
	v_bitop3_b32 v0, v1, v0, 32 bitop3:0x6c
	v_ashrrev_i32_e32 v2, 31, v12
	s_or_b32 s24, s0, 64
	s_bfe_u32 s23, s4, 0x20003
	s_ashr_i32 s7, s22, 8
	s_lshl_b32 s26, s6, 10
	s_lshl_b32 s5, s25, 10
	v_lshlrev_b32_e32 v3, 3, v8
	v_ashrrev_i32_e32 v1, 31, v0
	v_lshrrev_b32_e32 v2, 26, v2
	s_add_u32 s0, s47, s5
	v_and_b32_e32 v3, 0x7fff0, v3
	v_lshlrev_b32_e32 v4, 5, v8
	v_lshrrev_b32_e32 v1, 26, v1
	v_add_u32_e32 v2, v12, v2
	s_addc_u32 s1, s48, 0
	v_add_u32_e32 v3, v9, v3
	v_and_b32_e32 v10, 32, v4
	v_add_u32_e32 v1, v0, v1
	v_ashrrev_i32_e32 v14, 6, v2
	s_add_u32 s2, s45, s5
	v_lshl_or_b32 v3, v3, 12, v10
	v_ashrrev_i32_e32 v13, 6, v1
	v_lshlrev_b32_e32 v2, 3, v14
	v_and_b32_e32 v1, 0xc0, v1
	s_addc_u32 s3, s46, 0
	v_add_lshl_u32 v148, v3, v11, 1
	v_and_b32_e32 v2, 0x7fff0, v2
	v_lshlrev_b32_e32 v3, 5, v14
	v_sub_u32_e32 v0, v0, v1
	s_lshl_b32 s12, s24, 21
	s_lshl_b32 s13, s23, 21
	v_add_u32_e32 v2, v13, v2
	v_and_b32_e32 v15, 32, v3
	v_ashrrev_i16_sdwa v0, v188, sext(v0) dst_sel:DWORD dst_unused:UNUSED_PAD src0_sel:DWORD src1_sel:BYTE_0
	s_add_u32 s0, s0, s13
	v_lshl_or_b32 v2, v2, 12, v15
	v_bfe_i32 v16, v0, 0, 16
	s_addc_u32 s1, s1, 0
	s_add_i32 s27, s26, 0
	v_add_lshl_u32 v128, v2, v16, 1
	s_add_i32 m0, s27, 0x10000
	v_mov_b32_e32 v149, v129
	global_load_lds_dwordx4 v128, s[0:1]
	s_add_i32 m0, s27, 0x12000
	s_add_u32 s2, s2, s12
	global_load_lds_dwordx4 v148, s[0:1]
	s_addc_u32 s3, s3, 0
	s_mov_b32 m0, s27
	s_add_i32 s30, s27, 0x2000
	global_load_lds_dwordx4 v128, s[2:3]
	s_mov_b32 m0, s30
	s_add_u32 s12, s0, 0x100000
	global_load_lds_dwordx4 v148, s[2:3]
	s_addc_u32 s13, s1, 0
	s_add_i32 m0, s27, 0x14000
	v_lshl_add_u64 v[6:7], s[0:1], 0, v[128:129]
	global_load_lds_dwordx4 v128, s[12:13]
	s_add_i32 m0, s27, 0x16000
	v_lshl_add_u64 v[4:5], s[0:1], 0, v[148:149]
	global_load_lds_dwordx4 v148, s[12:13]
	s_add_u32 s12, s2, 0x100000
	s_addc_u32 s13, s3, 0
	s_add_i32 s31, s27, 0x4000
	s_mov_b32 m0, s31
	s_add_i32 s34, s27, 0x6000
	global_load_lds_dwordx4 v128, s[12:13]
	s_mov_b32 m0, s34
	v_lshl_add_u64 v[2:3], s[2:3], 0, v[128:129]
	global_load_lds_dwordx4 v148, s[12:13]
	s_cmp_lg_u32 s7, 1
	v_lshl_add_u64 v[0:1], s[2:3], 0, v[148:149]
	s_cbranch_scc1 .LBB0_1206
	s_barrier
	s_setprio 1

; #define PG8_STAGE(bufoff, gbase, voff) do { _Pragma("unroll") for (int _i = 0; _i < 2; ++_i) \
;         __builtin_amdgcn_global_load_lds((const unsigned*)((const char*)(gbase) + (voff)[_i]), (PG8_LAS unsigned*)(lds + (bufoff) + ldsw + _i * 8192), 16, 0, 0); } while (0)
; #define PG8_BAR __builtin_amdgcn_s_barrier()
; template <class Epi, class Sched, bool STAMP = false>
; __device__ __forceinline__ void gemm_phase(PG8_LAS unsigned char* lds, const Gemm g, const Sched& S, const Epi& E, unsigned long long* stamps) {
;     int tid_ = threadIdx.x; asm volatile("" : "+v"(tid_)); const int tid = tid_, wid = __builtin_amdgcn_readfirstlane(tid >> 6), lane = tid & 63, wr = wid >> 2, wc = wid & 3, fr = lane & 15, fq = lane >> 4;
;     const int K = g.K, nt = K / BK, LD = g.ld;
;     unsigned voffA[2], voffB[2];
; #pragma unroll
;     for (int i = 0; i < 2; ++i) { int R, C; stage_rc(tid * 16 + i * 8192, R, C); const int Rb = Epi::PERM ? ((R & ~31) + perm32(R & 31)) : R;
;         voffA[i] = (unsigned)(R * LD + C) * 2u; voffB[i] = (unsigned)(Rb * LD + C) * 2u; }
;     const size_t kstep = (size_t)(BK * 2);
;     const size_t hstep = (size_t)HALF * LD * 2;
;     const size_t tstep = 2 * hstep;
;     const unsigned ldsw = (unsigned)wid * 1024u;
;     const int aoff = lds_byte(wr * 64 + fr, fq * 8), boff = lds_byte(wc * 32 + fr, fq * 8);
;     ...
;     Unit cur, nxt; int ui = 0;
;     if (!S.next(0, cur)) return;
;     f32x4 acc[2][2][4][2];
; #pragma unroll
;     for (int a = 0; a < 2; ++a)
; #pragma unroll
;         for (int b = 0; b < 2; ++b)
; #pragma unroll
;             for (int m = 0; m < 4; ++m)
; #pragma unroll
;                 for (int n = 0; n < 2; ++n) acc[a][b][m][n] = (f32x4){0.f, 0.f, 0.f, 0.f};
;     bf16x8 At[4][2], B0[2][2], B1[2][2];
;     const char* cA = (const char*)g.A + (size_t)cur.pm * tstep; const char* cB = (const char*)g.Bt + (size_t)cur.pn * tstep;
;     S.a_ready(cur);
;     PG8_STAGE(PG8_SB(0, 0), cB, voffB); PG8_STAGE(PG8_SA(0, 0), cA, voffA); PG8_STAGE(PG8_SB(0, 1), cB + hstep, voffB); PG8_STAGE(PG8_SA(0, 1), cA + hstep, voffA);
;     if (wr == 1) PG8_BAR;
; __global__ void __launch_bounds__(512, 2) mega_fwd(Params prm) {
;     ...
;         case 1: { GEMM_PRO; EpiBf<0> E; E.O = (bf16_t*)(ws + OFF_A); E.ldc = 2048; E.rowss = rs_mix; run_gemm(lds, XB, (const bf16_t*)(ws + OFF_WRW), 2048, 1024, E, T_P);
.LBB0_1332:
	s_and_b64 vcc, exec, s[2:3]
	s_cbranch_vccz .LBB0_1364
	s_mov_b32 s10, s87
	s_mov_b32 s36, s86
	s_add_u32 s37, s36, 0x2200000
	s_addc_u32 s40, s10, 0
	s_and_b64 s[0:1], s[34:35], exec
	s_cselect_b32 s0, 0x22000, 0
	s_add_u32 s0, s36, s0
	s_addc_u32 s1, s10, 0
	s_add_u32 s0, s0, 0x2060000
	s_addc_u32 s1, s1, 0
	s_add_u32 s2, s36, 0x5500000
	s_addc_u32 s3, s10, 0
	s_mov_b32 s41, s90
	v_mov_b32_e32 v0, v184
	s_cmpk_gt_i32 s41, 0x1ff
	v_readfirstlane_b32 s42, v0
	s_cbranch_scc1 .LBB0_1345
	v_lshlrev_b32_e32 v4, 4, v0
	v_add_u32_e32 v2, 0x2000, v4
	v_ashrrev_i32_e32 v1, 31, v2
	v_lshrrev_b32_e32 v1, 22, v1
	v_add_u32_e32 v1, v2, v1
	v_ashrrev_i32_e32 v1, 10, v1
	v_mul_i32_i24_e32 v3, 0x400, v1
	v_sub_u32_e32 v2, v2, v3
	v_lshrrev_b32_e32 v3, 4, v2
	v_bitop3_b32 v3, v3, v2, 32 bitop3:0x6c
	v_ashrrev_i32_e32 v2, 31, v3
	v_lshrrev_b32_e32 v2, 26, v2
	s_waitcnt lgkmcnt(0)
	v_add_u32_e32 v5, v3, v2
	v_lshlrev_b32_e32 v6, 3, v1
	v_ashrrev_i32_e32 v2, 6, v5
	v_and_b32_e32 v6, -16, v6
	v_add_u32_e32 v6, v2, v6
	v_and_b32_e32 v7, 3, v2
	s_mov_b32 s4, 0x1fffe0
	v_lshrrev_b32_e32 v8, 2, v6
	v_lshlrev_b32_e32 v9, 1, v6
	v_and_b32_e32 v5, 0xc0, v5
	v_and_or_b32 v7, v6, s4, v7
	v_and_b32_e32 v8, 4, v8
	v_and_b32_e32 v9, 24, v9
	v_sub_u32_e32 v3, v3, v5
	v_or3_b32 v7, v7, v8, v9
	v_lshlrev_b32_e32 v8, 5, v1
	v_ashrrev_i16_sdwa v3, v188, sext(v3) dst_sel:DWORD dst_unused:UNUSED_PAD src0_sel:DWORD src1_sel:BYTE_0
	v_and_b32_e32 v8, 32, v8
	v_bfe_i32 v3, v3, 0, 16
	v_add_lshl_u32 v5, v8, v3, 1
	v_lshl_add_u32 v148, v7, 11, v5
	v_lshl_add_u32 v150, v6, 11, v5
	v_bfe_i32 v5, v0, 27, 1
	v_lshrrev_b32_e32 v5, 22, v5
	v_add_u32_e32 v5, v4, v5
	v_and_b32_e32 v5, 0xfffffc00, v5
	v_sub_u32_e32 v4, v4, v5
	v_lshrrev_b32_e32 v5, 4, v4
	v_bitop3_b32 v6, v5, v4, 32 bitop3:0x6c
	v_ashrrev_i32_e32 v5, 31, v0
	v_lshrrev_b32_e32 v5, 26, v5
	v_ashrrev_i32_e32 v4, 31, v6
	v_add_u32_e32 v5, v0, v5
	v_lshrrev_b32_e32 v4, 26, v4
	v_ashrrev_i32_e32 v5, 6, v5
	v_add_u32_e32 v7, v6, v4
	v_lshlrev_b32_e32 v8, 3, v5
	v_ashrrev_i32_e32 v4, 6, v7
	v_and_b32_e32 v8, -16, v8
	v_add_u32_e32 v8, v4, v8
	v_and_b32_e32 v9, 3, v4
	s_ashr_i32 s44, s41, 31
	v_and_or_b32 v9, v8, s4, v9
	s_lshr_b32 s4, s44, 29
	s_add_i32 s4, s41, s4
	s_ashr_i32 s6, s42, 6
	s_ashr_i32 s7, s4, 3
	s_and_b32 s4, s4, -8
	s_ashr_i32 s5, s42, 8
	s_lshl_b32 s43, s6, 10
	s_sub_i32 s4, s41, s4
	s_cmp_lt_i32 s4, 0
	s_cselect_b32 s12, 0x41, 64
	s_mul_i32 s4, s12, s4
	s_add_i32 s4, s4, s7
	s_ashr_i32 s7, s4, 31
	s_lshr_b32 s7, s7, 26
	s_add_i32 s7, s4, s7
	s_ashr_i32 s12, s7, 6
	s_and_b32 s7, s7, 0xffc0
	s_sub_i32 s7, s4, s7
	s_bfe_i32 s4, s7, 0x80000
	s_bfe_u32 s4, s4, 0x3000c
	s_add_i32 s13, s7, s4
	s_bfe_i32 s4, s13, 0x80000
	s_and_b32 s13, s13, 0xf8
	s_sub_i32 s7, s7, s13
	s_lshl_b32 s12, s12, 3
	s_sext_i32_i16 s4, s4
	s_sext_i32_i8 s7, s7
	v_lshrrev_b32_e32 v10, 2, v8
	v_lshlrev_b32_e32 v11, 1, v8
	v_and_b32_e32 v7, 0xc0, v7
	s_lshr_b32 s4, s4, 3
	s_add_i32 s22, s12, s7
	v_and_b32_e32 v10, 4, v10
	v_and_b32_e32 v11, 24, v11
	v_sub_u32_e32 v6, v6, v7
	s_ashr_i32 s23, s22, 31
	s_bfe_i64 s[14:15], s[4:5], 0x100000
	v_or3_b32 v9, v9, v10, v11
	v_lshlrev_b32_e32 v10, 5, v5
	v_ashrrev_i16_sdwa v6, v188, sext(v6) dst_sel:DWORD dst_unused:UNUSED_PAD src0_sel:DWORD src1_sel:BYTE_0
	s_lshl_b64 s[12:13], s[22:23], 19
	s_lshl_b64 s[14:15], s[14:15], 19
	v_and_b32_e32 v10, 32, v10
	v_bfe_i32 v6, v6, 0, 16
	s_add_u32 s26, s36, s14
	v_add_lshl_u32 v7, v10, v6, 1
	s_addc_u32 s27, s10, s15
	s_add_i32 s23, s43, 0
	v_lshl_add_u32 v128, v9, 11, v7
	s_add_i32 m0, s23, 0x10000
	v_lshl_add_u32 v152, v8, 11, v7
	global_load_lds_dwordx4 v128, s[26:27]
	s_add_i32 m0, s23, 0x12000
	s_add_u32 s24, s37, s12
	global_load_lds_dwordx4 v148, s[26:27]
	s_addc_u32 s25, s40, s13
	s_mov_b32 m0, s23
	s_add_i32 s45, s23, 0x2000
	global_load_lds_dwordx4 v152, s[24:25]
	s_mov_b32 m0, s45
	s_add_u32 s12, s26, 0x40000
	global_load_lds_dwordx4 v150, s[24:25]
	s_addc_u32 s13, s27, 0
	s_add_i32 m0, s23, 0x14000
	s_nop 0
	global_load_lds_dwordx4 v128, s[12:13]
	s_add_i32 m0, s23, 0x16000
	s_nop 0
	global_load_lds_dwordx4 v148, s[12:13]
	s_add_u32 s12, s24, 0x40000
	s_addc_u32 s13, s25, 0
	s_add_i32 s46, s23, 0x4000
	s_mov_b32 m0, s46
	s_add_i32 s47, s23, 0x6000
	global_load_lds_dwordx4 v152, s[12:13]
	s_mov_b32 m0, s47
	s_cmp_lg_u32 s5, 1
	global_load_lds_dwordx4 v150, s[12:13]
	s_cbranch_scc1 .LBB0_1336
	s_barrier
	s_setprio 1

; #define PG8_STAGE(bufoff, gbase, voff) do { _Pragma("unroll") for (int _i = 0; _i < 2; ++_i) \
;         __builtin_amdgcn_global_load_lds((const unsigned*)((const char*)(gbase) + (voff)[_i]), (PG8_LAS unsigned*)(lds + (bufoff) + ldsw + _i * 8192), 16, 0, 0); } while (0)
; #define PG8_BAR __builtin_amdgcn_s_barrier()
; template <class Epi, class Sched, bool STAMP = false>
; __device__ __forceinline__ void gemm_phase(PG8_LAS unsigned char* lds, const Gemm g, const Sched& S, const Epi& E, unsigned long long* stamps) {
;     ...
;     for (int i = 0; i < 2; ++i) { int R, C; stage_rc(tid * 16 + i * 8192, R, C); const int Rb = Epi::PERM ? ((R & ~31) + perm32(R & 31)) : R;
;         voffA[i] = (unsigned)(R * LD + C) * 2u; voffB[i] = (unsigned)(Rb * LD + C) * 2u; }
;     const size_t kstep = (size_t)(BK * 2);
;     const size_t hstep = (size_t)HALF * LD * 2;
;     const size_t tstep = 2 * hstep;
;     const unsigned ldsw = (unsigned)wid * 1024u;
;     const int aoff = lds_byte(wr * 64 + fr, fq * 8), boff = lds_byte(wc * 32 + fr, fq * 8);
;     ...
;     Unit cur, nxt; int ui = 0;
;     if (!S.next(0, cur)) return;
;     f32x4 acc[2][2][4][2];
; #pragma unroll
;     for (int a = 0; a < 2; ++a)
; #pragma unroll
;         for (int b = 0; b < 2; ++b)
; #pragma unroll
;             for (int m = 0; m < 4; ++m)
; #pragma unroll
;                 for (int n = 0; n < 2; ++n) acc[a][b][m][n] = (f32x4){0.f, 0.f, 0.f, 0.f};
;     bf16x8 At[4][2], B0[2][2], B1[2][2];
;     const char* cA = (const char*)g.A + (size_t)cur.pm * tstep; const char* cB = (const char*)g.Bt + (size_t)cur.pn * tstep;
;     S.a_ready(cur);
;     PG8_STAGE(PG8_SB(0, 0), cB, voffB); PG8_STAGE(PG8_SA(0, 0), cA, voffA); PG8_STAGE(PG8_SB(0, 1), cB + hstep, voffB); PG8_STAGE(PG8_SA(0, 1), cA + hstep, voffA);
;     if (wr == 1) PG8_BAR;
; __device__ __forceinline__ void run_rw_sample_tasks(LAS unsigned char* lds, unsigned char* ws) {
;     const int t = bidx(); OneUnit S; S.valid = t < 128; const int u = (t >> 2) & 31, sl = t & 3; S.pm = 64 + (u >> 3); S.pn = u & 7;
;     pg8::Gemm g; g.A = (const bf16_t*)(ws + OFF_XB) + sl * 256; g.Bt = (const bf16_t*)(ws + OFF_WRW) + sl * 256; g.M = T_ALL; g.N = 2048; g.K = 256; g.ld = 1024;
;     EpiPartial EA; EA.PART = (float*)(ws + OFF_GPART) + (size_t)sl * 1024 * 2048; EA.ldp = 2048;
;     pg8::gemm_phase<EpiPartial, OneUnit, false>(lds, g, S, EA, nullptr);
.LBB0_1344:
	s_setprio 0
	v_readlane_b32 s46, v242, 24
	v_readlane_b32 s47, v242, 25
	v_readlane_b32 s39, v242, 28
	s_movk_i32 s58, 0xff60
	s_mov_b32 s38, 0x1ffff
	s_barrier
.LBB0_1345:
	s_add_u32 s4, s36, 0xbb00000
	s_mov_b32 s6, s90
	s_addc_u32 s5, s10, 0
	v_mov_b32_e32 v0, v184
	s_cmpk_gt_i32 s6, 0x7f
	s_nop 0
	v_readfirstlane_b32 s42, v0
	s_cbranch_scc1 .LBB0_1353
	v_lshlrev_b32_e32 v1, 4, v0
	v_add_u32_e32 v2, 0x2000, v1
	v_ashrrev_i32_e32 v3, 31, v2
	v_lshrrev_b32_e32 v3, 22, v3
	v_add_u32_e32 v3, v2, v3
	v_ashrrev_i32_e32 v3, 10, v3
	v_mul_i32_i24_e32 v4, 0x400, v3
	v_sub_u32_e32 v2, v2, v4
	v_lshrrev_b32_e32 v4, 4, v2
	v_bitop3_b32 v2, v4, v2, 32 bitop3:0x6c
	v_ashrrev_i32_e32 v4, 31, v2
	v_lshrrev_b32_e32 v4, 26, v4
	v_add_u32_e32 v4, v2, v4
	s_waitcnt lgkmcnt(0)
	v_lshrrev_b32_e32 v5, 6, v4
	v_lshlrev_b32_e32 v6, 3, v3
	v_and_b32_e32 v4, 0xc0, v4
	v_and_b32_e32 v6, 0x1ffff0, v6
	v_lshlrev_b32_e32 v3, 5, v3
	v_sub_u32_e32 v2, v2, v4
	v_add_u32_e32 v5, v5, v6
	v_and_b32_e32 v3, 32, v3
	v_ashrrev_i16_sdwa v2, v188, sext(v2) dst_sel:DWORD dst_unused:UNUSED_PAD src0_sel:DWORD src1_sel:BYTE_0
	v_lshl_or_b32 v3, v5, 10, v3
	v_bfe_i32 v2, v2, 0, 16
	v_add_lshl_u32 v148, v3, v2, 1
	v_bfe_i32 v2, v0, 27, 1
	v_lshrrev_b32_e32 v2, 22, v2
	v_add_u32_e32 v2, v1, v2
	v_and_b32_e32 v2, 0xfffffc00, v2
	v_sub_u32_e32 v1, v1, v2
	v_lshrrev_b32_e32 v2, 4, v1
	s_and_b32 s45, s6, 3
	s_bfe_u32 s7, s6, 0x20005
	s_ashr_i32 s14, s42, 6
	v_bitop3_b32 v1, v2, v1, 32 bitop3:0x6c
	v_ashrrev_i32_e32 v4, 31, v0
	s_or_b32 s44, s7, 64
	s_bfe_u32 s43, s6, 0x30002
	s_ashr_i32 s15, s42, 8
	s_lshl_b32 s46, s14, 10
	s_lshl_b32 s6, s45, 9
	v_ashrrev_i32_e32 v2, 31, v1
	v_lshrrev_b32_e32 v4, 26, v4
	s_add_u32 s7, s36, s6
	v_lshrrev_b32_e32 v2, 26, v2
	v_add_u32_e32 v4, v0, v4
	s_addc_u32 s10, s10, 0
	v_add_u32_e32 v2, v1, v2
	v_ashrrev_i32_e32 v4, 6, v4
	s_add_u32 s12, s37, s6
	v_lshrrev_b32_e32 v3, 6, v2
	v_lshlrev_b32_e32 v5, 3, v4
	v_and_b32_e32 v2, 0xc0, v2
	s_addc_u32 s13, s40, 0
	v_and_b32_e32 v5, 0x1ffff0, v5
	v_lshlrev_b32_e32 v4, 5, v4
	v_sub_u32_e32 v1, v1, v2
	s_lshl_b32 s16, s44, 19
	s_lshl_b32 s6, s43, 19
	v_add_u32_e32 v3, v3, v5
	v_and_b32_e32 v4, 32, v4
	v_ashrrev_i16_sdwa v1, v188, sext(v1) dst_sel:DWORD dst_unused:UNUSED_PAD src0_sel:DWORD src1_sel:BYTE_0
	s_add_u32 s6, s7, s6
	v_lshl_or_b32 v3, v3, 10, v4
	v_bfe_i32 v1, v1, 0, 16
	s_addc_u32 s7, s10, 0
	s_add_i32 s10, s46, 0
	v_add_lshl_u32 v128, v3, v1, 1
	s_add_i32 m0, s10, 0x10000
	s_nop 0
	global_load_lds_dwordx4 v128, s[6:7]
	s_add_i32 m0, s10, 0x12000
	s_add_u32 s12, s12, s16
	global_load_lds_dwordx4 v148, s[6:7]
	s_addc_u32 s13, s13, 0
	s_mov_b32 m0, s10
	s_add_i32 s47, s10, 0x2000
	global_load_lds_dwordx4 v128, s[12:13]
	s_mov_b32 m0, s47
	s_add_u32 s16, s6, 0x40000
	global_load_lds_dwordx4 v148, s[12:13]
	s_addc_u32 s17, s7, 0
	s_add_i32 m0, s10, 0x14000
	s_nop 0
	global_load_lds_dwordx4 v128, s[16:17]
	s_add_i32 m0, s10, 0x16000
	s_add_u32 s20, s12, 0x40000
	s_addc_u32 s21, s13, 0
	s_add_i32 s48, s10, 0x4000
	global_load_lds_dwordx4 v148, s[16:17]
	s_mov_b32 m0, s48
	s_add_i32 s49, s10, 0x6000
	global_load_lds_dwordx4 v128, s[20:21]
	s_mov_b32 m0, s49
	s_cmp_lg_u32 s15, 1
	global_load_lds_dwordx4 v148, s[20:21]
	s_cbranch_scc1 .LBB0_1348
	s_barrier
	s_setprio 1

; #define PG8_WAIT_V(n) asm volatile("s_waitcnt vmcnt(" #n ")" ::: "memory")
; #define PG8_BAR __builtin_amdgcn_s_barrier()
; template <class Epi, class Sched, bool STAMP = false>
; __device__ __forceinline__ void gemm_phase(PG8_LAS unsigned char* lds, const Gemm g, const Sched& S, const Epi& E, unsigned long long* stamps) {
;     ...
;     PG8_WAIT_V(0);
;     if (wr == 0) PG8_BAR;
;     PG8_BAR;
.LBB0_1352:
	s_setprio 0
	v_readlane_b32 s46, v242, 24
	v_readlane_b32 s47, v242, 25
	v_readlane_b32 s52, v242, 26
	v_readlane_b32 s29, v242, 27
	v_readlane_b32 s39, v242, 28
	s_mov_b32 s38, 0x1ffff
	s_mov_b32 s62, 0x1800000
	s_barrier
